# prefetch pointwise-GEMM weight fragments during LayerNorm stage of mixer
# baseline (speedup 1.0000x reference)
; #define LAS __attribute__((address_space(3)))
; __device__ __forceinline__ unsigned pk2(float lo, float hi) { unsigned r; asm("v_cvt_pk_bf16_f32 %0, %1, %2" : "=v"(r) : "v"(lo), "v"(hi)); return r; }
; __device__ __forceinline__ float bf_lo(unsigned w) { return __uint_as_float(w << 16); }
; __device__ __forceinline__ float bf_hi(unsigned w) { return __uint_as_float(w & 0xffff0000u); }
; __device__ __forceinline__ void mixer_chunk(KP p, LAS unsigned char* lds, int l, int chunk) {
;     ...
; #pragma unroll 1
;         for (int blk = 0; blk < 4; ++blk) {
;             const int t0 = 32 * tq + 8 * blk;
;             float a0[8], a1[8];
; #pragma unroll
;             for (int o = 0; o < 8; ++o) { a0[o] = bb[0]; a1[o] = bb[1]; }
; #pragma unroll
;             for (int r = 0; r < 38; ++r) {
;                 const unsigned yv = *(const LAS unsigned*)(Y + (t0 + r) * YLD + c); const float y0 = bf_lo(yv), y1 = bf_hi(yv);
; #pragma unroll
;                 for (int o = 0; o < 8; ++o) { const int j = r - o; if (j >= 0 && j <= 30) { a0[o] += w0[j] * y0; a1[o] += w1[j] * y1; } }
;             }
; #pragma unroll
;             for (int o = 0; o < 8; ++o) *(LAS unsigned*)(CO + (t0 + o) * YLD + c) = pk2(a0[o], a1[o]);
;         }
.LBB0_295:
	v_add_u32_e32 v67, s6, v0
	v_add_u32_e32 v68, 0x4200, v67
	ds_read2_b32 v[70:71], v68 offset1:132
	v_add_u32_e32 v72, 0x4600, v67
	ds_read2_b32 v[74:75], v72 offset0:8 offset1:140
	v_add_u32_e32 v76, 0x4a00, v67
	ds_read2_b32 v[78:79], v76 offset0:16 offset1:148
	s_waitcnt lgkmcnt(2)
	v_and_b32_e32 v69, 0xffff0000, v70
	v_lshlrev_b32_e32 v68, 16, v70
	v_add_u32_e32 v80, 0x4e00, v67
	s_waitcnt vmcnt(0)
	v_fma_f32 v68, v2, v68, v64
	v_fma_f32 v69, v3, v69, v65
	v_lshlrev_b32_e32 v70, 16, v71
	v_and_b32_e32 v71, 0xffff0000, v71
	ds_read2_b32 v[82:83], v80 offset0:24 offset1:156
	v_fmac_f32_e32 v68, v4, v70
	v_fmac_f32_e32 v69, v5, v71
	v_fma_f32 v70, v2, v70, v64
	v_fma_f32 v71, v3, v71, v65
	s_waitcnt lgkmcnt(2)
	v_lshlrev_b32_e32 v72, 16, v74
	v_and_b32_e32 v73, 0xffff0000, v74
	v_add_u32_e32 v84, 0x5200, v67
	v_fmac_f32_e32 v68, v6, v72
	v_fmac_f32_e32 v69, v7, v73
	v_fmac_f32_e32 v70, v4, v72
	v_fmac_f32_e32 v71, v5, v73
	v_fma_f32 v72, v2, v72, v64
	v_fma_f32 v73, v3, v73, v65
	v_lshlrev_b32_e32 v74, 16, v75
	v_and_b32_e32 v75, 0xffff0000, v75
	ds_read2_b32 v[84:85], v84 offset0:32 offset1:164
	v_fmac_f32_e32 v68, v8, v74
	v_fmac_f32_e32 v69, v9, v75
	v_fmac_f32_e32 v70, v6, v74
	v_fmac_f32_e32 v71, v7, v75
	v_fmac_f32_e32 v72, v4, v74
	v_fmac_f32_e32 v73, v5, v75
	v_fma_f32 v74, v2, v74, v64
	v_fma_f32 v75, v3, v75, v65
	s_waitcnt lgkmcnt(2)
	v_lshlrev_b32_e32 v76, 16, v78
	v_and_b32_e32 v77, 0xffff0000, v78
	v_fmac_f32_e32 v68, v10, v76
	v_fmac_f32_e32 v69, v11, v77
	v_fmac_f32_e32 v70, v8, v76
	v_fmac_f32_e32 v71, v9, v77
	v_fmac_f32_e32 v72, v6, v76
	v_fmac_f32_e32 v73, v7, v77
	v_fmac_f32_e32 v74, v4, v76
	v_fmac_f32_e32 v75, v5, v77
	v_fma_f32 v76, v2, v76, v64
	v_fma_f32 v77, v3, v77, v65
	v_lshlrev_b32_e32 v78, 16, v79
	v_and_b32_e32 v79, 0xffff0000, v79
	v_fmac_f32_e32 v68, v18, v78
	v_fmac_f32_e32 v69, v19, v79
	v_fmac_f32_e32 v70, v10, v78
	v_fmac_f32_e32 v71, v11, v79
	v_fmac_f32_e32 v72, v8, v78
	v_fmac_f32_e32 v73, v9, v79
	v_fmac_f32_e32 v74, v6, v78
	v_fmac_f32_e32 v75, v7, v79
	v_fmac_f32_e32 v76, v4, v78
	v_fmac_f32_e32 v77, v5, v79
	v_fma_f32 v78, v2, v78, v64
	v_fma_f32 v79, v3, v79, v65
	s_waitcnt lgkmcnt(1)
	v_lshlrev_b32_e32 v80, 16, v82
	v_and_b32_e32 v81, 0xffff0000, v82
	v_fmac_f32_e32 v68, v20, v80
	v_fmac_f32_e32 v69, v21, v81
	v_fmac_f32_e32 v70, v18, v80
	v_fmac_f32_e32 v71, v19, v81
	v_fmac_f32_e32 v72, v10, v80
	v_fmac_f32_e32 v73, v11, v81
	v_fmac_f32_e32 v74, v8, v80
	v_fmac_f32_e32 v75, v9, v81
	v_fmac_f32_e32 v76, v6, v80
	v_fmac_f32_e32 v77, v7, v81
	v_fmac_f32_e32 v78, v4, v80
	v_fmac_f32_e32 v79, v5, v81
	v_fma_f32 v80, v2, v80, v64
	v_fma_f32 v81, v3, v81, v65
	v_lshlrev_b32_e32 v82, 16, v83
	v_and_b32_e32 v83, 0xffff0000, v83
	v_fmac_f32_e32 v68, v22, v82
	v_fmac_f32_e32 v69, v23, v83
	v_fmac_f32_e32 v70, v20, v82
	v_fmac_f32_e32 v71, v21, v83
	v_fmac_f32_e32 v72, v18, v82
	v_fmac_f32_e32 v73, v19, v83
	v_fmac_f32_e32 v74, v10, v82
	v_fmac_f32_e32 v75, v11, v83
	v_fmac_f32_e32 v76, v8, v82
	v_fmac_f32_e32 v77, v9, v83
	v_fmac_f32_e32 v78, v6, v82
	v_fmac_f32_e32 v79, v7, v83
	v_fmac_f32_e32 v80, v4, v82
	v_fmac_f32_e32 v81, v5, v83
	v_fma_f32 v82, v2, v82, v64
	v_fma_f32 v83, v3, v83, v65
	s_waitcnt lgkmcnt(0)
	v_lshlrev_b32_e32 v86, 16, v84
	v_and_b32_e32 v84, 0xffff0000, v84
	v_fmac_f32_e32 v68, v12, v86
	v_fmac_f32_e32 v69, v13, v84
	v_fmac_f32_e32 v70, v22, v86
	v_fmac_f32_e32 v71, v23, v84
	v_fmac_f32_e32 v72, v20, v86
	v_fmac_f32_e32 v73, v21, v84
	v_fmac_f32_e32 v74, v18, v86
	v_fmac_f32_e32 v75, v19, v84
	v_fmac_f32_e32 v76, v10, v86
	v_fmac_f32_e32 v77, v11, v84
	v_fmac_f32_e32 v78, v8, v86
	v_fmac_f32_e32 v79, v9, v84
	v_fmac_f32_e32 v80, v6, v86
	v_fmac_f32_e32 v81, v7, v84
	v_fmac_f32_e32 v82, v4, v86
	v_fmac_f32_e32 v83, v5, v84
	v_lshlrev_b32_e32 v84, 16, v85
	v_and_b32_e32 v85, 0xffff0000, v85
	v_fmac_f32_e32 v68, v14, v84
	v_fmac_f32_e32 v70, v12, v84
	v_fmac_f32_e32 v72, v22, v84
	v_fmac_f32_e32 v74, v20, v84
	v_fmac_f32_e32 v76, v18, v84
	v_fmac_f32_e32 v78, v10, v84
	v_fmac_f32_e32 v80, v8, v84
	v_fmac_f32_e32 v82, v6, v84
	v_add_u32_e32 v84, 0x5600, v67
	v_fmac_f32_e32 v69, v15, v85
	v_fmac_f32_e32 v71, v13, v85
	v_fmac_f32_e32 v73, v23, v85
	v_fmac_f32_e32 v75, v21, v85
	v_fmac_f32_e32 v77, v19, v85
	v_fmac_f32_e32 v79, v11, v85
	v_fmac_f32_e32 v81, v9, v85
	v_fmac_f32_e32 v83, v7, v85
	ds_read2_b32 v[84:85], v84 offset0:40 offset1:172
	s_addk_i32 s6, 0x1080
	s_cmp_eq_u32 s6, 0
	s_waitcnt lgkmcnt(0)
	v_lshlrev_b32_e32 v86, 16, v84
	v_and_b32_e32 v84, 0xffff0000, v84
	v_fmac_f32_e32 v68, v16, v86
	v_fmac_f32_e32 v69, v17, v84
	v_fmac_f32_e32 v70, v14, v86
	v_fmac_f32_e32 v71, v15, v84
	v_fmac_f32_e32 v72, v12, v86
	v_fmac_f32_e32 v73, v13, v84
	v_fmac_f32_e32 v74, v22, v86
	v_fmac_f32_e32 v75, v23, v84
	v_fmac_f32_e32 v76, v20, v86
	v_fmac_f32_e32 v77, v21, v84
	v_fmac_f32_e32 v78, v18, v86
	v_fmac_f32_e32 v79, v19, v84
	v_fmac_f32_e32 v80, v10, v86
	v_fmac_f32_e32 v81, v11, v84
	v_fmac_f32_e32 v82, v8, v86
	v_fmac_f32_e32 v83, v9, v84
	v_lshlrev_b32_e32 v84, 16, v85
	v_and_b32_e32 v85, 0xffff0000, v85
	v_fmac_f32_e32 v68, v26, v84
	v_fmac_f32_e32 v70, v16, v84
	v_fmac_f32_e32 v72, v14, v84
	v_fmac_f32_e32 v74, v12, v84
	v_fmac_f32_e32 v76, v22, v84
	v_fmac_f32_e32 v78, v20, v84
	v_fmac_f32_e32 v80, v18, v84
	v_fmac_f32_e32 v82, v10, v84
	v_add_u32_e32 v84, 0x5a00, v67
	v_fmac_f32_e32 v69, v27, v85
	v_fmac_f32_e32 v71, v17, v85
	v_fmac_f32_e32 v73, v15, v85
	v_fmac_f32_e32 v75, v13, v85
	v_fmac_f32_e32 v77, v23, v85
	v_fmac_f32_e32 v79, v21, v85
	v_fmac_f32_e32 v81, v19, v85
	v_fmac_f32_e32 v83, v11, v85
	ds_read2_b32 v[84:85], v84 offset0:48 offset1:180
	s_waitcnt lgkmcnt(0)
; #define LAS __attribute__((address_space(3)))
; __device__ __forceinline__ float bf_lo(unsigned w) { return __uint_as_float(w << 16); }
; __device__ __forceinline__ float bf_hi(unsigned w) { return __uint_as_float(w & 0xffff0000u); }
; __device__ __forceinline__ void mixer_chunk(KP p, LAS unsigned char* lds, int l, int chunk) {
;     ...
; #pragma unroll
;             for (int r = 0; r < 38; ++r) {
;                 const unsigned yv = *(const LAS unsigned*)(Y + (t0 + r) * YLD + c); const float y0 = bf_lo(yv), y1 = bf_hi(yv);
; #pragma unroll
;                 for (int o = 0; o < 8; ++o) { const int j = r - o; if (j >= 0 && j <= 30) { a0[o] += w0[j] * y0; a1[o] += w1[j] * y1; } }
;             }
	v_lshlrev_b32_e32 v86, 16, v84
	v_and_b32_e32 v84, 0xffff0000, v84
	v_fmac_f32_e32 v68, v28, v86
	v_fmac_f32_e32 v69, v29, v84
	v_fmac_f32_e32 v70, v26, v86
	v_fmac_f32_e32 v71, v27, v84
	v_fmac_f32_e32 v72, v16, v86
	v_fmac_f32_e32 v73, v17, v84
	v_fmac_f32_e32 v74, v14, v86
	v_fmac_f32_e32 v75, v15, v84
	v_fmac_f32_e32 v76, v12, v86
	v_fmac_f32_e32 v77, v13, v84
	v_fmac_f32_e32 v78, v22, v86
	v_fmac_f32_e32 v79, v23, v84
	v_fmac_f32_e32 v80, v20, v86
	v_fmac_f32_e32 v81, v21, v84
	v_fmac_f32_e32 v82, v18, v86
	v_fmac_f32_e32 v83, v19, v84
	v_lshlrev_b32_e32 v84, 16, v85
	v_and_b32_e32 v85, 0xffff0000, v85
	v_fmac_f32_e32 v68, v24, v84
	v_fmac_f32_e32 v70, v28, v84
	v_fmac_f32_e32 v72, v26, v84
	v_fmac_f32_e32 v74, v16, v84
	v_fmac_f32_e32 v76, v14, v84
	v_fmac_f32_e32 v78, v12, v84
	v_fmac_f32_e32 v80, v22, v84
	v_fmac_f32_e32 v82, v20, v84
	v_add_u32_e32 v84, 0x5e00, v67
	v_fmac_f32_e32 v69, v25, v85
	v_fmac_f32_e32 v71, v29, v85
	v_fmac_f32_e32 v73, v27, v85
	v_fmac_f32_e32 v75, v17, v85
	v_fmac_f32_e32 v77, v15, v85
	v_fmac_f32_e32 v79, v13, v85
	v_fmac_f32_e32 v81, v23, v85
	v_fmac_f32_e32 v83, v21, v85
	ds_read2_b32 v[84:85], v84 offset0:56 offset1:188
	s_waitcnt lgkmcnt(0)
	v_lshlrev_b32_e32 v86, 16, v84
	v_and_b32_e32 v84, 0xffff0000, v84
	v_fmac_f32_e32 v68, v34, v86
	v_fmac_f32_e32 v69, v35, v84
	v_fmac_f32_e32 v70, v24, v86
	v_fmac_f32_e32 v71, v25, v84
	v_fmac_f32_e32 v72, v28, v86
	v_fmac_f32_e32 v73, v29, v84
	v_fmac_f32_e32 v74, v26, v86
	v_fmac_f32_e32 v75, v27, v84
	v_fmac_f32_e32 v76, v16, v86
	v_fmac_f32_e32 v77, v17, v84
	v_fmac_f32_e32 v78, v14, v86
	v_fmac_f32_e32 v79, v15, v84
	v_fmac_f32_e32 v80, v12, v86
	v_fmac_f32_e32 v81, v13, v84
	v_fmac_f32_e32 v82, v22, v86
	v_fmac_f32_e32 v83, v23, v84
	v_lshlrev_b32_e32 v84, 16, v85
	v_and_b32_e32 v85, 0xffff0000, v85
	v_fmac_f32_e32 v68, v36, v84
	v_fmac_f32_e32 v70, v34, v84
	v_fmac_f32_e32 v72, v24, v84
	v_fmac_f32_e32 v74, v28, v84
	v_fmac_f32_e32 v76, v26, v84
	v_fmac_f32_e32 v78, v16, v84
	v_fmac_f32_e32 v80, v14, v84
	v_fmac_f32_e32 v82, v12, v84
	v_add_u32_e32 v84, 0x6200, v67
	v_fmac_f32_e32 v69, v37, v85
	v_fmac_f32_e32 v71, v35, v85
	v_fmac_f32_e32 v73, v25, v85
	v_fmac_f32_e32 v75, v29, v85
	v_fmac_f32_e32 v77, v27, v85
	v_fmac_f32_e32 v79, v17, v85
	v_fmac_f32_e32 v81, v15, v85
	v_fmac_f32_e32 v83, v13, v85
	ds_read2_b32 v[84:85], v84 offset0:64 offset1:196
	s_waitcnt lgkmcnt(0)
	v_lshlrev_b32_e32 v86, 16, v84
	v_and_b32_e32 v84, 0xffff0000, v84
	v_fmac_f32_e32 v68, v30, v86
	v_fmac_f32_e32 v69, v31, v84
	v_fmac_f32_e32 v70, v36, v86
	v_fmac_f32_e32 v71, v37, v84
	v_fmac_f32_e32 v72, v34, v86
	v_fmac_f32_e32 v73, v35, v84
	v_fmac_f32_e32 v74, v24, v86
	v_fmac_f32_e32 v75, v25, v84
	v_fmac_f32_e32 v76, v28, v86
	v_fmac_f32_e32 v77, v29, v84
	v_fmac_f32_e32 v78, v26, v86
	v_fmac_f32_e32 v79, v27, v84
	v_fmac_f32_e32 v80, v16, v86
	v_fmac_f32_e32 v81, v17, v84
	v_fmac_f32_e32 v82, v14, v86
	v_fmac_f32_e32 v83, v15, v84
	v_lshlrev_b32_e32 v84, 16, v85
	v_and_b32_e32 v85, 0xffff0000, v85
	v_fmac_f32_e32 v68, v32, v84
	v_fmac_f32_e32 v70, v30, v84
	v_fmac_f32_e32 v72, v36, v84
	v_fmac_f32_e32 v74, v34, v84
	v_fmac_f32_e32 v76, v24, v84
	v_fmac_f32_e32 v78, v28, v84
	v_fmac_f32_e32 v80, v26, v84
	v_fmac_f32_e32 v82, v16, v84
	v_add_u32_e32 v84, 0x6600, v67
	v_fmac_f32_e32 v69, v33, v85
	v_fmac_f32_e32 v71, v31, v85
	v_fmac_f32_e32 v73, v37, v85
	v_fmac_f32_e32 v75, v35, v85
	v_fmac_f32_e32 v77, v25, v85
	v_fmac_f32_e32 v79, v29, v85
	v_fmac_f32_e32 v81, v27, v85
	v_fmac_f32_e32 v83, v17, v85
	ds_read2_b32 v[84:85], v84 offset0:72 offset1:204
	s_waitcnt lgkmcnt(0)
	v_lshlrev_b32_e32 v86, 16, v84
	v_and_b32_e32 v84, 0xffff0000, v84
	v_fmac_f32_e32 v68, v42, v86
	v_fmac_f32_e32 v69, v43, v84
	v_fmac_f32_e32 v70, v32, v86
	v_fmac_f32_e32 v71, v33, v84
	v_fmac_f32_e32 v72, v30, v86
	v_fmac_f32_e32 v73, v31, v84
	v_fmac_f32_e32 v74, v36, v86
	v_fmac_f32_e32 v75, v37, v84
	v_fmac_f32_e32 v76, v34, v86
	v_fmac_f32_e32 v77, v35, v84
	v_fmac_f32_e32 v78, v24, v86
	v_fmac_f32_e32 v79, v25, v84
	v_fmac_f32_e32 v80, v28, v86
	v_fmac_f32_e32 v81, v29, v84
	v_fmac_f32_e32 v82, v26, v86
	v_fmac_f32_e32 v83, v27, v84
	v_lshlrev_b32_e32 v84, 16, v85
	v_and_b32_e32 v85, 0xffff0000, v85
	v_fmac_f32_e32 v68, v44, v84
	v_fmac_f32_e32 v70, v42, v84
	v_fmac_f32_e32 v72, v32, v84
	v_fmac_f32_e32 v74, v30, v84
	v_fmac_f32_e32 v76, v36, v84
	v_fmac_f32_e32 v78, v34, v84
	v_fmac_f32_e32 v80, v24, v84
	v_fmac_f32_e32 v82, v28, v84
	v_add_u32_e32 v84, 0x6a00, v67
	v_fmac_f32_e32 v69, v45, v85
	v_fmac_f32_e32 v71, v43, v85
	v_fmac_f32_e32 v73, v33, v85
	v_fmac_f32_e32 v75, v31, v85
	v_fmac_f32_e32 v77, v37, v85
	v_fmac_f32_e32 v79, v35, v85
	v_fmac_f32_e32 v81, v25, v85
	v_fmac_f32_e32 v83, v29, v85
	ds_read2_b32 v[84:85], v84 offset0:80 offset1:212
	s_waitcnt lgkmcnt(0)
	v_lshlrev_b32_e32 v86, 16, v84
	v_and_b32_e32 v84, 0xffff0000, v84
	v_fmac_f32_e32 v68, v46, v86
	v_fmac_f32_e32 v69, v47, v84
	v_fmac_f32_e32 v70, v44, v86
	v_fmac_f32_e32 v71, v45, v84
	v_fmac_f32_e32 v72, v42, v86
	v_fmac_f32_e32 v73, v43, v84
	v_fmac_f32_e32 v74, v32, v86
	v_fmac_f32_e32 v75, v33, v84
	v_fmac_f32_e32 v76, v30, v86
	v_fmac_f32_e32 v77, v31, v84
	v_fmac_f32_e32 v78, v36, v86
	v_fmac_f32_e32 v79, v37, v84
	v_fmac_f32_e32 v80, v34, v86
	v_fmac_f32_e32 v81, v35, v84
	v_fmac_f32_e32 v82, v24, v86
	v_fmac_f32_e32 v83, v25, v84
	v_lshlrev_b32_e32 v84, 16, v85
	v_and_b32_e32 v85, 0xffff0000, v85
	v_fmac_f32_e32 v68, v38, v84
	v_fmac_f32_e32 v70, v46, v84
	v_fmac_f32_e32 v72, v44, v84
	v_fmac_f32_e32 v74, v42, v84
	v_fmac_f32_e32 v76, v32, v84
	v_fmac_f32_e32 v78, v30, v84
	v_fmac_f32_e32 v80, v36, v84
	v_fmac_f32_e32 v82, v34, v84
	v_add_u32_e32 v84, 0x6e00, v67
	v_fmac_f32_e32 v69, v39, v85
	v_fmac_f32_e32 v71, v47, v85
	v_fmac_f32_e32 v73, v45, v85
	v_fmac_f32_e32 v75, v43, v85
	v_fmac_f32_e32 v77, v33, v85
	v_fmac_f32_e32 v79, v31, v85
	v_fmac_f32_e32 v81, v37, v85
	v_fmac_f32_e32 v83, v35, v85
	ds_read2_b32 v[84:85], v84 offset0:88 offset1:220
	s_waitcnt lgkmcnt(0)
; #define LAS __attribute__((address_space(3)))
; __device__ __forceinline__ unsigned pk2(float lo, float hi) { unsigned r; asm("v_cvt_pk_bf16_f32 %0, %1, %2" : "=v"(r) : "v"(lo), "v"(hi)); return r; }
; __device__ __forceinline__ float bf_lo(unsigned w) { return __uint_as_float(w << 16); }
; __device__ __forceinline__ float bf_hi(unsigned w) { return __uint_as_float(w & 0xffff0000u); }
; __device__ __forceinline__ void mixer_chunk(KP p, LAS unsigned char* lds, int l, int chunk) {
;     ...
; #pragma unroll
;             for (int r = 0; r < 38; ++r) {
;                 const unsigned yv = *(const LAS unsigned*)(Y + (t0 + r) * YLD + c); const float y0 = bf_lo(yv), y1 = bf_hi(yv);
; #pragma unroll
;                 for (int o = 0; o < 8; ++o) { const int j = r - o; if (j >= 0 && j <= 30) { a0[o] += w0[j] * y0; a1[o] += w1[j] * y1; } }
;             }
; #pragma unroll
;             for (int o = 0; o < 8; ++o) *(LAS unsigned*)(CO + (t0 + o) * YLD + c) = pk2(a0[o], a1[o]);
	v_lshlrev_b32_e32 v86, 16, v84
	v_and_b32_e32 v84, 0xffff0000, v84
	v_fmac_f32_e32 v68, v40, v86
	v_fmac_f32_e32 v69, v41, v84
	v_fmac_f32_e32 v70, v38, v86
	v_fmac_f32_e32 v71, v39, v84
	v_fmac_f32_e32 v72, v46, v86
	v_fmac_f32_e32 v73, v47, v84
	v_fmac_f32_e32 v74, v44, v86
	v_fmac_f32_e32 v75, v45, v84
	v_fmac_f32_e32 v76, v42, v86
	v_fmac_f32_e32 v77, v43, v84
	v_fmac_f32_e32 v78, v32, v86
	v_fmac_f32_e32 v79, v33, v84
	v_fmac_f32_e32 v80, v30, v86
	v_fmac_f32_e32 v81, v31, v84
	v_fmac_f32_e32 v82, v36, v86
	v_fmac_f32_e32 v83, v37, v84
	v_lshlrev_b32_e32 v84, 16, v85
	v_and_b32_e32 v85, 0xffff0000, v85
	v_fmac_f32_e32 v68, v56, v84
	v_fmac_f32_e32 v70, v40, v84
	v_fmac_f32_e32 v72, v38, v84
	v_fmac_f32_e32 v74, v46, v84
	v_fmac_f32_e32 v76, v44, v84
	v_fmac_f32_e32 v78, v42, v84
	v_fmac_f32_e32 v80, v32, v84
	v_fmac_f32_e32 v82, v30, v84
	v_add_u32_e32 v84, 0x7200, v67
	v_fmac_f32_e32 v69, v57, v85
	v_fmac_f32_e32 v71, v41, v85
	v_fmac_f32_e32 v73, v39, v85
	v_fmac_f32_e32 v75, v47, v85
	v_fmac_f32_e32 v77, v45, v85
	v_fmac_f32_e32 v79, v43, v85
	v_fmac_f32_e32 v81, v33, v85
	v_fmac_f32_e32 v83, v31, v85
	ds_read2_b32 v[84:85], v84 offset0:96 offset1:228
	s_waitcnt lgkmcnt(0)
	v_lshlrev_b32_e32 v86, 16, v84
	v_and_b32_e32 v84, 0xffff0000, v84
	v_fmac_f32_e32 v68, v48, v86
	v_fmac_f32_e32 v69, v49, v84
	v_fmac_f32_e32 v70, v56, v86
	v_fmac_f32_e32 v71, v57, v84
	v_fmac_f32_e32 v72, v40, v86
	v_fmac_f32_e32 v73, v41, v84
	v_fmac_f32_e32 v74, v38, v86
	v_fmac_f32_e32 v75, v39, v84
	v_fmac_f32_e32 v76, v46, v86
	v_fmac_f32_e32 v77, v47, v84
	v_fmac_f32_e32 v78, v44, v86
	v_fmac_f32_e32 v79, v45, v84
	v_fmac_f32_e32 v80, v42, v86
	v_fmac_f32_e32 v81, v43, v84
	v_fmac_f32_e32 v82, v32, v86
	v_fmac_f32_e32 v83, v33, v84
	v_lshlrev_b32_e32 v84, 16, v85
	v_and_b32_e32 v85, 0xffff0000, v85
	v_fmac_f32_e32 v68, v50, v84
	v_fmac_f32_e32 v70, v48, v84
	v_fmac_f32_e32 v72, v56, v84
	v_fmac_f32_e32 v74, v40, v84
	v_fmac_f32_e32 v76, v38, v84
	v_fmac_f32_e32 v78, v46, v84
	v_fmac_f32_e32 v80, v44, v84
	v_fmac_f32_e32 v82, v42, v84
	v_add_u32_e32 v84, 0x7600, v67
	v_fmac_f32_e32 v69, v51, v85
	v_fmac_f32_e32 v71, v49, v85
	v_fmac_f32_e32 v73, v57, v85
	v_fmac_f32_e32 v75, v41, v85
	v_fmac_f32_e32 v77, v39, v85
	v_fmac_f32_e32 v79, v47, v85
	v_fmac_f32_e32 v81, v45, v85
	v_fmac_f32_e32 v83, v43, v85
	ds_read2_b32 v[84:85], v84 offset0:104 offset1:236
	s_waitcnt lgkmcnt(0)
	v_lshlrev_b32_e32 v86, 16, v84
	v_and_b32_e32 v84, 0xffff0000, v84
	v_fmac_f32_e32 v68, v52, v86
	v_fmac_f32_e32 v69, v53, v84
	v_fmac_f32_e32 v70, v50, v86
	v_fmac_f32_e32 v71, v51, v84
	v_fmac_f32_e32 v72, v48, v86
	v_fmac_f32_e32 v73, v49, v84
	v_fmac_f32_e32 v74, v56, v86
	v_fmac_f32_e32 v75, v57, v84
	v_fmac_f32_e32 v76, v40, v86
	v_fmac_f32_e32 v77, v41, v84
	v_fmac_f32_e32 v78, v38, v86
	v_fmac_f32_e32 v79, v39, v84
	v_fmac_f32_e32 v80, v46, v86
	v_fmac_f32_e32 v81, v47, v84
	v_fmac_f32_e32 v82, v44, v86
	v_fmac_f32_e32 v83, v45, v84
	v_lshlrev_b32_e32 v84, 16, v85
	v_and_b32_e32 v85, 0xffff0000, v85
	v_fmac_f32_e32 v68, v54, v84
	v_fmac_f32_e32 v70, v52, v84
	v_fmac_f32_e32 v72, v50, v84
	v_fmac_f32_e32 v74, v48, v84
	v_fmac_f32_e32 v76, v56, v84
	v_fmac_f32_e32 v78, v40, v84
	v_fmac_f32_e32 v80, v38, v84
	v_fmac_f32_e32 v82, v46, v84
	v_add_u32_e32 v84, 0x7a00, v67
	v_fmac_f32_e32 v69, v55, v85
	v_fmac_f32_e32 v71, v53, v85
	v_fmac_f32_e32 v73, v51, v85
	v_fmac_f32_e32 v75, v49, v85
	v_fmac_f32_e32 v77, v57, v85
	v_fmac_f32_e32 v79, v41, v85
	v_fmac_f32_e32 v81, v39, v85
	v_fmac_f32_e32 v83, v47, v85
	ds_read2_b32 v[84:85], v84 offset0:112 offset1:244
	s_waitcnt lgkmcnt(0)
	v_lshlrev_b32_e32 v86, 16, v84
	v_and_b32_e32 v84, 0xffff0000, v84
	v_fmac_f32_e32 v68, v58, v86
	v_fmac_f32_e32 v69, v59, v84
	v_fmac_f32_e32 v70, v54, v86
	v_fmac_f32_e32 v71, v55, v84
	v_fmac_f32_e32 v72, v52, v86
	v_fmac_f32_e32 v73, v53, v84
	v_fmac_f32_e32 v74, v50, v86
	v_fmac_f32_e32 v75, v51, v84
	v_fmac_f32_e32 v76, v48, v86
	v_fmac_f32_e32 v77, v49, v84
	v_fmac_f32_e32 v78, v56, v86
	v_fmac_f32_e32 v79, v57, v84
	v_fmac_f32_e32 v80, v40, v86
	v_fmac_f32_e32 v81, v41, v84
	v_fmac_f32_e32 v82, v38, v86
	v_fmac_f32_e32 v83, v39, v84
	v_lshlrev_b32_e32 v84, 16, v85
	v_and_b32_e32 v85, 0xffff0000, v85
	v_fmac_f32_e32 v68, v60, v84
	v_fmac_f32_e32 v70, v58, v84
	v_fmac_f32_e32 v72, v54, v84
	v_fmac_f32_e32 v74, v52, v84
	v_fmac_f32_e32 v76, v50, v84
	v_fmac_f32_e32 v78, v48, v84
	v_fmac_f32_e32 v80, v56, v84
	v_fmac_f32_e32 v82, v40, v84
	v_add_u32_e32 v84, 0x7e00, v67
	v_fmac_f32_e32 v69, v61, v85
	v_fmac_f32_e32 v71, v59, v85
	v_fmac_f32_e32 v73, v55, v85
	v_fmac_f32_e32 v75, v53, v85
	v_fmac_f32_e32 v77, v51, v85
	v_fmac_f32_e32 v79, v49, v85
	v_fmac_f32_e32 v81, v57, v85
	v_fmac_f32_e32 v83, v41, v85
	ds_read2_b32 v[84:85], v84 offset0:120 offset1:252
	s_waitcnt lgkmcnt(0)
	v_lshlrev_b32_e32 v86, 16, v84
	v_and_b32_e32 v84, 0xffff0000, v84
	v_fmac_f32_e32 v69, v63, v84
	v_fmac_f32_e32 v70, v60, v86
	v_fmac_f32_e32 v71, v61, v84
	v_fmac_f32_e32 v72, v58, v86
	v_fmac_f32_e32 v73, v59, v84
	v_fmac_f32_e32 v74, v54, v86
	v_fmac_f32_e32 v75, v55, v84
	v_fmac_f32_e32 v76, v52, v86
	v_fmac_f32_e32 v77, v53, v84
	v_fmac_f32_e32 v78, v50, v86
	v_fmac_f32_e32 v79, v51, v84
	v_fmac_f32_e32 v80, v48, v86
	v_fmac_f32_e32 v81, v49, v84
	v_fmac_f32_e32 v82, v56, v86
	v_fmac_f32_e32 v83, v57, v84
	v_lshlrev_b32_e32 v84, 16, v85
	v_and_b32_e32 v85, 0xffff0000, v85
	v_fmac_f32_e32 v70, v62, v84
	v_fmac_f32_e32 v72, v60, v84
	v_fmac_f32_e32 v74, v58, v84
	v_fmac_f32_e32 v76, v54, v84
	v_fmac_f32_e32 v78, v52, v84
	v_fmac_f32_e32 v80, v50, v84
	v_fmac_f32_e32 v82, v48, v84
	v_add_u32_e32 v84, 0x8400, v67
	v_fmac_f32_e32 v71, v63, v85
	v_fmac_f32_e32 v73, v61, v85
	v_fmac_f32_e32 v75, v59, v85
	v_fmac_f32_e32 v77, v55, v85
	v_fmac_f32_e32 v79, v53, v85
	v_fmac_f32_e32 v81, v51, v85
	v_fmac_f32_e32 v83, v49, v85
	ds_read2_b32 v[84:85], v84 offset1:132
	v_fmac_f32_e32 v68, v62, v86
	v_cvt_pk_bf16_f32 v68, v68, v69
	v_add_u32_e32 v69, 0x19a00, v67
	ds_write_b32 v69, v68
	s_waitcnt lgkmcnt(1)
; #define LAS __attribute__((address_space(3)))
; __device__ __forceinline__ unsigned pk2(float lo, float hi) { unsigned r; asm("v_cvt_pk_bf16_f32 %0, %1, %2" : "=v"(r) : "v"(lo), "v"(hi)); return r; }
; __device__ __forceinline__ float bf_lo(unsigned w) { return __uint_as_float(w << 16); }
; __device__ __forceinline__ float bf_hi(unsigned w) { return __uint_as_float(w & 0xffff0000u); }
; __device__ __forceinline__ void mixer_chunk(KP p, LAS unsigned char* lds, int l, int chunk) {
;     ...
; #pragma unroll
;             for (int r = 0; r < 38; ++r) {
;                 const unsigned yv = *(const LAS unsigned*)(Y + (t0 + r) * YLD + c); const float y0 = bf_lo(yv), y1 = bf_hi(yv);
; #pragma unroll
;                 for (int o = 0; o < 8; ++o) { const int j = r - o; if (j >= 0 && j <= 30) { a0[o] += w0[j] * y0; a1[o] += w1[j] * y1; } }
;             }
; #pragma unroll
;             for (int o = 0; o < 8; ++o) *(LAS unsigned*)(CO + (t0 + o) * YLD + c) = pk2(a0[o], a1[o]);
;         }
;     }
;     __syncthreads();
;     u32x4 sq[6], sk[4];
; #pragma unroll
;     for (int i = 0; i < 6; ++i) { const int q = tid + 512 * i, r = q / 24, pc = q % 24; sq[i] = *(const u32x4*)(zb + (size_t)(c0 + r) * DIN_P + ZC_CQ + 8 * pc); }
; #pragma unroll
;     for (int i = 0; i < 4; ++i) { const int q = tid + 512 * i, r = q >> 4, pc = q & 15; sk[i] = *(const u32x4*)(zb + (size_t)(c0 + r) * DIN_P + ZC_CKV + 8 * pc); }
;     {
;         const f32x4 lg = *(const f32x4*)(p->conv_ln_g + l * 256 + 4 * lane), lb = *(const f32x4*)(p->conv_ln_b + l * 256 + 4 * lane);
	v_lshlrev_b32_e32 v86, 16, v84
	v_and_b32_e32 v84, 0xffff0000, v84
	v_fmac_f32_e32 v73, v63, v84
	v_fmac_f32_e32 v74, v60, v86
	v_fmac_f32_e32 v75, v61, v84
	v_fmac_f32_e32 v76, v58, v86
	v_fmac_f32_e32 v77, v59, v84
	v_fmac_f32_e32 v78, v54, v86
	v_fmac_f32_e32 v79, v55, v84
	v_fmac_f32_e32 v80, v52, v86
	v_fmac_f32_e32 v81, v53, v84
	v_fmac_f32_e32 v82, v50, v86
	v_fmac_f32_e32 v83, v51, v84
	v_lshlrev_b32_e32 v84, 16, v85
	v_and_b32_e32 v85, 0xffff0000, v85
	v_fmac_f32_e32 v74, v62, v84
	v_fmac_f32_e32 v76, v60, v84
	v_fmac_f32_e32 v78, v58, v84
	v_fmac_f32_e32 v80, v54, v84
	v_fmac_f32_e32 v82, v52, v84
	v_add_u32_e32 v84, 0x8800, v67
	v_fmac_f32_e32 v75, v63, v85
	v_fmac_f32_e32 v77, v61, v85
	v_fmac_f32_e32 v79, v59, v85
	v_fmac_f32_e32 v81, v55, v85
	v_fmac_f32_e32 v83, v53, v85
	ds_read2_b32 v[84:85], v84 offset0:8 offset1:140
	v_fmac_f32_e32 v72, v62, v86
	v_cvt_pk_bf16_f32 v68, v70, v71
	v_add_u32_e32 v69, 0x19c10, v67
	ds_write_b32 v69, v68
	s_waitcnt lgkmcnt(1)
	v_lshlrev_b32_e32 v86, 16, v84
	v_and_b32_e32 v84, 0xffff0000, v84
	v_fmac_f32_e32 v77, v63, v84
	v_fmac_f32_e32 v78, v60, v86
	v_fmac_f32_e32 v79, v61, v84
	v_fmac_f32_e32 v80, v58, v86
	v_fmac_f32_e32 v81, v59, v84
	v_fmac_f32_e32 v82, v54, v86
	v_fmac_f32_e32 v83, v55, v84
	v_lshlrev_b32_e32 v84, 16, v85
	v_and_b32_e32 v85, 0xffff0000, v85
	v_fmac_f32_e32 v78, v62, v84
	v_fmac_f32_e32 v80, v60, v84
	v_fmac_f32_e32 v82, v58, v84
	v_add_u32_e32 v84, 0x8c00, v67
	v_fmac_f32_e32 v79, v63, v85
	v_fmac_f32_e32 v81, v61, v85
	v_fmac_f32_e32 v83, v59, v85
	ds_read2_b32 v[84:85], v84 offset0:16 offset1:148
	v_cvt_pk_bf16_f32 v68, v72, v73
	v_add_u32_e32 v69, 0x19e20, v67
	ds_write_b32 v69, v68
	v_cvt_pk_bf16_f32 v68, v74, v75
	v_add_u32_e32 v69, 0x1a030, v67
	v_fmac_f32_e32 v76, v62, v86
	ds_write_b32 v69, v68
	v_cvt_pk_bf16_f32 v68, v76, v77
	v_add_u32_e32 v69, 0x1a240, v67
	s_waitcnt lgkmcnt(2)
	v_lshlrev_b32_e32 v86, 16, v84
	v_and_b32_e32 v84, 0xffff0000, v84
	ds_write_b32 v69, v68
	v_cvt_pk_bf16_f32 v68, v78, v79
	v_add_u32_e32 v69, 0x1a450, v67
	v_fmac_f32_e32 v80, v62, v86
	v_fmac_f32_e32 v81, v63, v84
	v_fmac_f32_e32 v82, v60, v86
	v_fmac_f32_e32 v83, v61, v84
	v_lshlrev_b32_e32 v84, 16, v85
	v_and_b32_e32 v85, 0xffff0000, v85
	ds_write_b32 v69, v68
	v_cvt_pk_bf16_f32 v68, v80, v81
	v_add_u32_e32 v69, 0x1a660, v67
	v_add_u32_e32 v67, 0x1a870, v67
	v_fmac_f32_e32 v83, v63, v85
	v_fmac_f32_e32 v82, v62, v84
	ds_write_b32 v69, v68
	v_cvt_pk_bf16_f32 v68, v82, v83
	ds_write_b32 v67, v68
	s_cbranch_scc0 .LBB0_295
	v_mul_hi_i32 v0, v204, s63
	v_lshrrev_b32_e32 v2, 31, v0
	v_ashrrev_i32_e32 v0, 2, v0
	v_add_u32_e32 v74, v0, v2
	v_mul_lo_u32 v0, v74, 24
	v_sub_u32_e32 v75, v204, v0
	v_add_u32_e32 v0, s25, v74
	v_mov_b64_e32 v[38:39], s[44:45]
	v_mad_i64_i32 v[2:3], s[6:7], v0, s65, v[38:39]
	v_mul_hi_i32 v0, v206, s63
	v_lshrrev_b32_e32 v6, 31, v0
	v_ashrrev_i32_e32 v0, 2, v0
	v_add_u32_e32 v76, v0, v6
	v_mul_lo_u32 v0, v76, 24
	v_sub_u32_e32 v77, v206, v0
	v_add_u32_e32 v0, s25, v76
	v_mad_i64_i32 v[6:7], s[6:7], v0, s65, v[38:39]
	v_mul_hi_i32 v0, v212, s63
	v_lshrrev_b32_e32 v10, 31, v0
	v_ashrrev_i32_e32 v0, 2, v0
	v_add_u32_e32 v78, v0, v10
	v_mul_lo_u32 v0, v78, 24
	v_sub_u32_e32 v79, v212, v0
	v_add_u32_e32 v0, s25, v78
	v_mad_i64_i32 v[10:11], s[6:7], v0, s65, v[38:39]
	v_mul_hi_i32 v0, v211, s63
	v_lshrrev_b32_e32 v14, 31, v0
	v_ashrrev_i32_e32 v0, 2, v0
	v_add_u32_e32 v80, v0, v14
	v_mul_lo_u32 v0, v80, 24
	v_sub_u32_e32 v81, v211, v0
	v_add_u32_e32 v0, s25, v80
	v_mad_i64_i32 v[14:15], s[6:7], v0, s65, v[38:39]
	v_mul_hi_i32 v0, v210, s63
	v_lshrrev_b32_e32 v18, 31, v0
	v_ashrrev_i32_e32 v0, 2, v0
	v_add_u32_e32 v82, v0, v18
	v_mul_lo_u32 v0, v82, 24
	v_sub_u32_e32 v83, v210, v0
	v_add_u32_e32 v0, s25, v82
	v_add_u32_e32 v218, 0xa00, v204
	v_mad_i64_i32 v[18:19], s[6:7], v0, s65, v[38:39]
	v_mul_hi_i32 v0, v218, s63
	v_lshrrev_b32_e32 v22, 31, v0
	v_ashrrev_i32_e32 v0, 2, v0
	s_waitcnt lgkmcnt(0)
	s_barrier
	v_add_u32_e32 v84, v0, v22
	s_load_dwordx4 s[40:43], s[0:1], 0x30
	v_mul_lo_u32 v0, v84, 24
	v_sub_u32_e32 v85, v218, v0
	v_add_u32_e32 v0, s25, v84
	v_ashrrev_i32_e32 v86, 4, v204
	v_ashrrev_i32_e32 v88, 4, v206
	v_ashrrev_i32_e32 v89, 4, v212
	v_ashrrev_i32_e32 v90, 4, v211
	v_mad_i64_i32 v[22:23], s[6:7], v0, s65, v[38:39]
	v_add_u32_e32 v0, s25, v86
	v_add_u32_e32 v30, s25, v88
	v_add_u32_e32 v34, s25, v89
	v_add_u32_e32 v40, s25, v90
	v_and_b32_e32 v87, 0x78, v209
	v_mad_i64_i32 v[26:27], s[6:7], v0, s65, v[38:39]
	v_mad_i64_i32 v[30:31], s[6:7], v30, s65, v[38:39]
	v_mad_i64_i32 v[34:35], s[6:7], v34, s65, v[38:39]
	v_mad_i64_i32 v[38:39], s[6:7], v40, s65, v[38:39]
	v_lshlrev_b32_e32 v0, 1, v87
	s_waitcnt lgkmcnt(0)
; #define LAS __attribute__((address_space(3)))
; __device__ __forceinline__ float bf_lo(unsigned w) { return __uint_as_float(w << 16); }
; __device__ __forceinline__ float bf_hi(unsigned w) { return __uint_as_float(w & 0xffff0000u); }
; template <int NKS, int NNT>
; __device__ __forceinline__ void wgemm(f32x4 (&acc)[8][NNT], const LAS bf16_t* A, const int lda, const bf16_t* Bp, const int ldb) {
;     u32x4 bf[NNT][NKS];
; #pragma unroll
;     for (int nt = 0; nt < NNT; ++nt) ldfr(bf[nt], Bp + (size_t)(16 * nt) * ldb);
; #pragma unroll
;     for (int nt = 0; nt < NNT; ++nt) pin(bf[nt]);
; __device__ __forceinline__ void mixer_chunk(KP p, LAS unsigned char* lds, int l, int chunk) {
;     ...
;     u32x4 sq[6], sk[4];
; #pragma unroll
;     for (int i = 0; i < 6; ++i) { const int q = tid + 512 * i, r = q / 24, pc = q % 24; sq[i] = *(const u32x4*)(zb + (size_t)(c0 + r) * DIN_P + ZC_CQ + 8 * pc); }
; #pragma unroll
;     for (int i = 0; i < 4; ++i) { const int q = tid + 512 * i, r = q >> 4, pc = q & 15; sk[i] = *(const u32x4*)(zb + (size_t)(c0 + r) * DIN_P + ZC_CKV + 8 * pc); }
;     {
;         const f32x4 lg = *(const f32x4*)(p->conv_ln_g + l * 256 + 4 * lane), lb = *(const f32x4*)(p->conv_ln_b + l * 256 + 4 * lane);
; #pragma unroll 1
;         for (int half = 0; half < 2; ++half) {
;             f32x4 x[8]; float s[8];
; #pragma unroll
;             for (int i = 0; i < 8; ++i) { const u32x2 v = *(const LAS u32x2*)(CO + (16 * w + 8 * half + i) * YLD + 4 * lane);
;                 x[i] = (f32x4){bf_lo(v.x), bf_hi(v.x), bf_lo(v.y), bf_hi(v.y)}; s[i] = (x[i][0] + x[i][1]) + (x[i][2] + x[i][3]); }
	s_add_u32 s6, s40, s36
	v_lshlrev_b32_e32 v4, 3, v75
	v_lshlrev_b32_e32 v8, 3, v77
	v_lshlrev_b32_e32 v12, 3, v79
	v_lshlrev_b32_e32 v16, 3, v81
	v_lshlrev_b32_e32 v20, 3, v83
	v_lshlrev_b32_e32 v24, 3, v85
	v_lshl_add_u64 v[26:27], v[26:27], 0, v[0:1]
	v_lshl_add_u64 v[30:31], v[30:31], 0, v[0:1]
	v_lshl_add_u64 v[34:35], v[34:35], 0, v[0:1]
	v_lshl_add_u64 v[38:39], v[38:39], 0, v[0:1]
	s_addc_u32 s7, s41, s37
	v_lshlrev_b32_e32 v0, 2, v66
	v_ashrrev_i32_e32 v5, 31, v4
	v_ashrrev_i32_e32 v9, 31, v8
	v_ashrrev_i32_e32 v13, 31, v12
	v_ashrrev_i32_e32 v17, 31, v16
	v_ashrrev_i32_e32 v21, 31, v20
	v_ashrrev_i32_e32 v25, 31, v24
	global_load_dwordx4 v[42:45], v0, s[6:7]
	s_add_u32 s6, s42, s36
	v_lshl_add_u64 v[2:3], v[4:5], 1, v[2:3]
	v_lshl_add_u64 v[6:7], v[8:9], 1, v[6:7]
	v_lshl_add_u64 v[10:11], v[12:13], 1, v[10:11]
	v_lshl_add_u64 v[14:15], v[16:17], 1, v[14:15]
	v_lshl_add_u64 v[18:19], v[20:21], 1, v[18:19]
	v_lshl_add_u64 v[22:23], v[24:25], 1, v[22:23]
	s_addc_u32 s7, s43, s37
	global_load_dwordx4 v[2:5], v[2:3], off offset:1024
	v_and_b32_e32 v50, 64, v193
	global_load_dwordx4 v[6:9], v[6:7], off offset:1024
	v_add_u32_e32 v50, 64, v50
	global_load_dwordx4 v[10:13], v[10:11], off offset:1024
	v_xor_b32_e32 v51, 1, v193
	global_load_dwordx4 v[14:17], v[14:15], off offset:1024
	v_cmp_lt_i32_e32 vcc, v51, v50
	global_load_dwordx4 v[18:21], v[18:19], off offset:1024
	s_lshl_b32 s88, s55, 4
	global_load_dwordx4 v[22:25], v[22:23], off offset:1024
	v_cndmask_b32_e32 v51, v193, v51, vcc
	global_load_dwordx4 v[26:29], v[26:27], off offset:1408
	v_lshlrev_b32_e32 v213, 2, v51
	global_load_dwordx4 v[30:33], v[30:31], off offset:1408
	v_xor_b32_e32 v51, 2, v193
	global_load_dwordx4 v[34:37], v[34:35], off offset:1408
	v_cmp_lt_i32_e32 vcc, v51, v50
	global_load_dwordx4 v[38:41], v[38:39], off offset:1408
	s_mov_b64 s[40:41], -1
	global_load_dwordx4 v[46:49], v0, s[6:7]
	v_and_b32_e32 v220, 15, v204
	v_and_b32_e32 v221, 48, v205
	v_lshl_add_u32 v220, v220, 9, v221
	v_mov_b32_e32 v221, s55
	v_lshl_add_u32 v220, v221, 14, v220
	v_add_u32_e32 v221, 0x2000, v220
	v_readlane_b32 s100, v252, 8
	v_readlane_b32 s101, v252, 9
	s_nop 4
	global_load_dwordx4 v[120:123], v220, s[100:101]
	global_load_dwordx4 v[124:127], v220, s[100:101] offset:64
	global_load_dwordx4 v[128:131], v220, s[100:101] offset:128
	global_load_dwordx4 v[132:135], v220, s[100:101] offset:192
	global_load_dwordx4 v[136:139], v220, s[100:101] offset:256
	global_load_dwordx4 v[140:143], v220, s[100:101] offset:320
	global_load_dwordx4 v[144:147], v220, s[100:101] offset:384
	global_load_dwordx4 v[148:151], v220, s[100:101] offset:448
	global_load_dwordx4 v[152:155], v221, s[100:101]
	global_load_dwordx4 v[168:171], v221, s[100:101] offset:64
	global_load_dwordx4 v[172:175], v221, s[100:101] offset:128
	global_load_dwordx4 v[176:179], v221, s[100:101] offset:192
	global_load_dwordx4 v[180:183], v221, s[100:101] offset:256
	global_load_dwordx4 v[184:187], v221, s[100:101] offset:320
	global_load_dwordx4 v[226:229], v221, s[100:101] offset:384
	global_load_dwordx4 v[230:233], v221, s[100:101] offset:448
	v_cndmask_b32_e32 v51, v193, v51, vcc
	v_lshlrev_b32_e32 v214, 2, v51
	v_xor_b32_e32 v51, 4, v193
	v_cmp_lt_i32_e32 vcc, v51, v50
	v_lshl_add_u32 v0, v66, 1, s69
	s_mov_b32 s6, 0
	v_cndmask_b32_e32 v51, v193, v51, vcc
	v_lshlrev_b32_e32 v91, 2, v51
	v_xor_b32_e32 v51, 8, v193
	v_cmp_lt_i32_e32 vcc, v51, v50
	s_nop 1
	v_cndmask_b32_e32 v51, v193, v51, vcc
	v_lshlrev_b32_e32 v92, 2, v51
	v_xor_b32_e32 v51, 16, v193
	v_cmp_lt_i32_e32 vcc, v51, v50
	s_nop 1
	v_cndmask_b32_e32 v51, v193, v51, vcc
	v_lshlrev_b32_e32 v207, 2, v51
	v_xor_b32_e32 v51, 32, v193
	v_cmp_lt_i32_e32 vcc, v51, v50
	s_nop 1
	v_cndmask_b32_e32 v50, v193, v51, vcc
	v_lshlrev_b32_e32 v208, 2, v50
.LBB0_297:
	s_or_b32 s6, s6, s88
	s_mulk_i32 s6, 0x210
	v_cndmask_b32_e64 v50, 0, 1, s[40:41]
	v_add_u32_e32 v110, s6, v0
	v_cmp_ne_u32_e32 vcc, 1, v50
	ds_read2_b64 v[50:53], v110 offset1:66
	v_add_u32_e32 v93, 0x800, v110
	ds_read2_b64 v[66:69], v93 offset0:140 offset1:206
	s_mov_b32 s6, 8
	s_mov_b64 s[40:41], 0
	s_waitcnt lgkmcnt(1)
	v_lshlrev_b32_e32 v65, 16, v51
	v_lshlrev_b32_e32 v64, 16, v50
	v_and_b32_e32 v71, 0xffff0000, v51
	v_and_b32_e32 v70, 0xffff0000, v50
	v_pk_add_f32 v[50:51], v[64:65], v[70:71]
	v_lshlrev_b32_e32 v63, 16, v53
	v_lshlrev_b32_e32 v62, 16, v52
	v_and_b32_e32 v73, 0xffff0000, v53
	v_and_b32_e32 v72, 0xffff0000, v52
	v_add_f32_e32 v104, v50, v51
	v_pk_add_f32 v[50:51], v[62:63], v[72:73]
	s_waitcnt lgkmcnt(0)
	v_and_b32_e32 v103, 0xffff0000, v69
	v_add_f32_e32 v105, v50, v51
	ds_read2_b64 v[50:53], v110 offset0:132 offset1:198
	v_and_b32_e32 v102, 0xffff0000, v68
	s_and_b64 vcc, exec, vcc
	s_waitcnt lgkmcnt(0)
	v_lshlrev_b32_e32 v61, 16, v51
	v_lshlrev_b32_e32 v60, 16, v50
	v_and_b32_e32 v95, 0xffff0000, v51
	v_and_b32_e32 v94, 0xffff0000, v50
	v_pk_add_f32 v[50:51], v[60:61], v[94:95]
	v_lshlrev_b32_e32 v59, 16, v53
	v_lshlrev_b32_e32 v58, 16, v52
	v_and_b32_e32 v97, 0xffff0000, v53
	v_and_b32_e32 v96, 0xffff0000, v52
	v_add_f32_e32 v106, v50, v51
	v_pk_add_f32 v[50:51], v[58:59], v[96:97]
	s_nop 0
	v_add_f32_e32 v107, v50, v51
	ds_read2_b64 v[50:53], v93 offset0:8 offset1:74
	s_waitcnt lgkmcnt(0)
; #define LAS __attribute__((address_space(3)))
; __device__ __forceinline__ float bf_lo(unsigned w) { return __uint_as_float(w << 16); }
; __device__ __forceinline__ float bf_hi(unsigned w) { return __uint_as_float(w & 0xffff0000u); }
; __device__ __forceinline__ void mixer_chunk(KP p, LAS unsigned char* lds, int l, int chunk) {
;     ...
; #pragma unroll 1
;         for (int half = 0; half < 2; ++half) {
;             f32x4 x[8]; float s[8];
; #pragma unroll
;             for (int i = 0; i < 8; ++i) { const u32x2 v = *(const LAS u32x2*)(CO + (16 * w + 8 * half + i) * YLD + 4 * lane);
;                 x[i] = (f32x4){bf_lo(v.x), bf_hi(v.x), bf_lo(v.y), bf_hi(v.y)}; s[i] = (x[i][0] + x[i][1]) + (x[i][2] + x[i][3]); }
; #pragma unroll
;             for (int o = 1; o < 64; o <<= 1)
; #pragma unroll
;                 for (int i = 0; i < 8; ++i) s[i] += __shfl_xor(s[i], o);
; #pragma unroll
;             for (int i = 0; i < 8; ++i) { x[i] = x[i] - s[i] * (1.0f / 256.0f); s[i] = (x[i][0] * x[i][0] + x[i][1] * x[i][1]) + (x[i][2] * x[i][2] + x[i][3] * x[i][3]); }
; #pragma unroll
;             for (int o = 1; o < 64; o <<= 1)
; #pragma unroll
;                 for (int i = 0; i < 8; ++i) s[i] += __shfl_xor(s[i], o);
	v_lshlrev_b32_e32 v57, 16, v51
	v_lshlrev_b32_e32 v56, 16, v50
	v_and_b32_e32 v99, 0xffff0000, v51
	v_and_b32_e32 v98, 0xffff0000, v50
	v_pk_add_f32 v[50:51], v[56:57], v[98:99]
	v_lshlrev_b32_e32 v55, 16, v53
	v_lshlrev_b32_e32 v54, 16, v52
	v_and_b32_e32 v101, 0xffff0000, v53
	v_and_b32_e32 v100, 0xffff0000, v52
	v_add_f32_e32 v108, v50, v51
	v_pk_add_f32 v[50:51], v[54:55], v[100:101]
	v_lshlrev_b32_e32 v53, 16, v67
	v_lshlrev_b32_e32 v52, 16, v66
	v_and_b32_e32 v67, 0xffff0000, v67
	v_and_b32_e32 v66, 0xffff0000, v66
	v_add_f32_e32 v109, v50, v51
	v_pk_add_f32 v[50:51], v[52:53], v[66:67]
	s_nop 0
	v_add_f32_e32 v111, v50, v51
	v_lshlrev_b32_e32 v51, 16, v69
	v_lshlrev_b32_e32 v50, 16, v68
	v_pk_add_f32 v[68:69], v[50:51], v[102:103]
	s_nop 0
	v_add_f32_e32 v68, v68, v69
	ds_bpermute_b32 v69, v213, v104
	s_waitcnt lgkmcnt(0)
	v_add_f32_e32 v69, v104, v69
	ds_bpermute_b32 v104, v213, v105
	s_waitcnt lgkmcnt(0)
	v_add_f32_e32 v104, v105, v104
	ds_bpermute_b32 v105, v213, v106
	s_waitcnt lgkmcnt(0)
	v_add_f32_e32 v105, v106, v105
	ds_bpermute_b32 v106, v213, v107
	s_waitcnt lgkmcnt(0)
	v_add_f32_e32 v106, v107, v106
	ds_bpermute_b32 v107, v213, v108
	s_waitcnt lgkmcnt(0)
	v_add_f32_e32 v107, v108, v107
	ds_bpermute_b32 v108, v213, v109
	s_waitcnt lgkmcnt(0)
	v_add_f32_e32 v108, v109, v108
	ds_bpermute_b32 v109, v213, v111
	s_waitcnt lgkmcnt(0)
	v_add_f32_e32 v109, v111, v109
	ds_bpermute_b32 v111, v213, v68
	s_waitcnt lgkmcnt(0)
	v_add_f32_e32 v68, v68, v111
	ds_bpermute_b32 v111, v214, v69
	s_waitcnt lgkmcnt(0)
	v_add_f32_e32 v69, v69, v111
	ds_bpermute_b32 v111, v214, v104
	s_waitcnt lgkmcnt(0)
	v_add_f32_e32 v104, v104, v111
	ds_bpermute_b32 v111, v214, v105
	s_waitcnt lgkmcnt(0)
	v_add_f32_e32 v105, v105, v111
	ds_bpermute_b32 v111, v214, v106
	s_waitcnt lgkmcnt(0)
	v_add_f32_e32 v106, v106, v111
	ds_bpermute_b32 v111, v214, v107
	s_waitcnt lgkmcnt(0)
	v_add_f32_e32 v107, v107, v111
	ds_bpermute_b32 v111, v214, v108
	s_waitcnt lgkmcnt(0)
	v_add_f32_e32 v108, v108, v111
	ds_bpermute_b32 v111, v214, v109
	s_waitcnt lgkmcnt(0)
	v_add_f32_e32 v109, v109, v111
	ds_bpermute_b32 v111, v214, v68
	s_waitcnt lgkmcnt(0)
	v_add_f32_e32 v68, v68, v111
	ds_bpermute_b32 v111, v91, v69
	s_waitcnt lgkmcnt(0)
	v_add_f32_e32 v69, v69, v111
	ds_bpermute_b32 v111, v91, v104
	s_waitcnt lgkmcnt(0)
	v_add_f32_e32 v104, v104, v111
	ds_bpermute_b32 v111, v91, v105
	s_waitcnt lgkmcnt(0)
	v_add_f32_e32 v105, v105, v111
	ds_bpermute_b32 v111, v91, v106
	s_waitcnt lgkmcnt(0)
	v_add_f32_e32 v106, v106, v111
	ds_bpermute_b32 v111, v91, v107
	s_waitcnt lgkmcnt(0)
	v_add_f32_e32 v107, v107, v111
	ds_bpermute_b32 v111, v91, v108
	s_waitcnt lgkmcnt(0)
	v_add_f32_e32 v108, v108, v111
	ds_bpermute_b32 v111, v91, v109
	s_waitcnt lgkmcnt(0)
	v_add_f32_e32 v109, v109, v111
	ds_bpermute_b32 v111, v91, v68
	s_waitcnt lgkmcnt(0)
	v_add_f32_e32 v68, v68, v111
	ds_bpermute_b32 v111, v92, v69
	s_waitcnt lgkmcnt(0)
	v_add_f32_e32 v69, v69, v111
	ds_bpermute_b32 v111, v92, v104
	s_waitcnt lgkmcnt(0)
	v_add_f32_e32 v104, v104, v111
	ds_bpermute_b32 v111, v92, v105
	s_waitcnt lgkmcnt(0)
	v_add_f32_e32 v105, v105, v111
	ds_bpermute_b32 v111, v92, v106
	s_waitcnt lgkmcnt(0)
	v_add_f32_e32 v106, v106, v111
	ds_bpermute_b32 v111, v92, v107
	s_waitcnt lgkmcnt(0)
	v_add_f32_e32 v107, v107, v111
	ds_bpermute_b32 v111, v92, v108
	s_waitcnt lgkmcnt(0)
	v_add_f32_e32 v108, v108, v111
	ds_bpermute_b32 v111, v92, v109
	s_waitcnt lgkmcnt(0)
	v_add_f32_e32 v109, v109, v111
	ds_bpermute_b32 v111, v92, v68
	s_waitcnt lgkmcnt(0)
	v_add_f32_e32 v68, v68, v111
	ds_bpermute_b32 v111, v207, v69
	s_waitcnt lgkmcnt(0)
	v_add_f32_e32 v69, v69, v111
	ds_bpermute_b32 v111, v207, v104
	s_waitcnt lgkmcnt(0)
	v_add_f32_e32 v104, v104, v111
	ds_bpermute_b32 v111, v207, v105
	s_waitcnt lgkmcnt(0)
	v_add_f32_e32 v105, v105, v111
	ds_bpermute_b32 v111, v207, v106
	s_waitcnt lgkmcnt(0)
	v_add_f32_e32 v106, v106, v111
	ds_bpermute_b32 v111, v207, v107
	s_waitcnt lgkmcnt(0)
	v_add_f32_e32 v107, v107, v111
	ds_bpermute_b32 v111, v207, v108
	s_waitcnt lgkmcnt(0)
	v_add_f32_e32 v108, v108, v111
	ds_bpermute_b32 v111, v207, v109
	s_waitcnt lgkmcnt(0)
	v_add_f32_e32 v109, v109, v111
	ds_bpermute_b32 v111, v207, v68
	s_waitcnt lgkmcnt(0)
	v_add_f32_e32 v68, v68, v111
	ds_bpermute_b32 v111, v208, v69
	s_waitcnt lgkmcnt(0)
	v_add_f32_e32 v69, v69, v111
	ds_bpermute_b32 v111, v208, v104
	v_fmac_f32_e32 v70, 0xbb800000, v69
	v_fmac_f32_e32 v71, 0xbb800000, v69
	v_fmac_f32_e32 v65, 0xbb800000, v69
	v_fmac_f32_e32 v64, 0xbb800000, v69
	s_waitcnt lgkmcnt(0)
	v_add_f32_e32 v111, v104, v111
	ds_bpermute_b32 v104, v208, v105
	v_fmac_f32_e32 v72, 0xbb800000, v111
	v_fmac_f32_e32 v73, 0xbb800000, v111
	v_fmac_f32_e32 v63, 0xbb800000, v111
	v_fmac_f32_e32 v62, 0xbb800000, v111
	s_waitcnt lgkmcnt(0)
	v_add_f32_e32 v112, v105, v104
	ds_bpermute_b32 v104, v208, v106
	v_mov_b32_e32 v105, v71
	v_fmac_f32_e32 v94, 0xbb800000, v112
	v_fmac_f32_e32 v95, 0xbb800000, v112
	v_fmac_f32_e32 v61, 0xbb800000, v112
	s_waitcnt lgkmcnt(0)
	v_add_f32_e32 v113, v106, v104
	ds_bpermute_b32 v104, v208, v107
	v_fmac_f32_e32 v60, 0xbb800000, v112
	v_fmac_f32_e32 v96, 0xbb800000, v113
	v_fmac_f32_e32 v97, 0xbb800000, v113
	v_fmac_f32_e32 v59, 0xbb800000, v113
	s_waitcnt lgkmcnt(0)
	v_add_f32_e32 v114, v107, v104
	ds_bpermute_b32 v104, v208, v108
	v_fmac_f32_e32 v58, 0xbb800000, v113
	v_fmac_f32_e32 v98, 0xbb800000, v114
	v_fmac_f32_e32 v99, 0xbb800000, v114
	v_fmac_f32_e32 v57, 0xbb800000, v114
	s_waitcnt lgkmcnt(0)
	v_add_f32_e32 v115, v108, v104
	ds_bpermute_b32 v104, v208, v109
	v_mov_b32_e32 v108, v61
	v_mov_b32_e32 v61, v94
	v_mov_b32_e32 v94, v59
	v_mov_b32_e32 v59, v96
	s_waitcnt lgkmcnt(0)
; #define LAS __attribute__((address_space(3)))
; __device__ __forceinline__ float bf_lo(unsigned w) { return __uint_as_float(w << 16); }
; __device__ __forceinline__ float bf_hi(unsigned w) { return __uint_as_float(w & 0xffff0000u); }
; __device__ __forceinline__ void mixer_chunk(KP p, LAS unsigned char* lds, int l, int chunk) {
;     ...
;             for (int i = 0; i < 8; ++i) { const u32x2 v = *(const LAS u32x2*)(CO + (16 * w + 8 * half + i) * YLD + 4 * lane);
;                 x[i] = (f32x4){bf_lo(v.x), bf_hi(v.x), bf_lo(v.y), bf_hi(v.y)}; s[i] = (x[i][0] + x[i][1]) + (x[i][2] + x[i][3]); }
; #pragma unroll
;             for (int o = 1; o < 64; o <<= 1)
; #pragma unroll
;                 for (int i = 0; i < 8; ++i) s[i] += __shfl_xor(s[i], o);
; #pragma unroll
;             for (int i = 0; i < 8; ++i) { x[i] = x[i] - s[i] * (1.0f / 256.0f); s[i] = (x[i][0] * x[i][0] + x[i][1] * x[i][1]) + (x[i][2] * x[i][2] + x[i][3] * x[i][3]); }
; #pragma unroll
;             for (int o = 1; o < 64; o <<= 1)
; #pragma unroll
;                 for (int i = 0; i < 8; ++i) s[i] += __shfl_xor(s[i], o);
	v_add_f32_e32 v116, v109, v104
	ds_bpermute_b32 v104, v208, v68
	v_mov_b32_e32 v109, v95
	v_mov_b32_e32 v95, v97
	v_fmac_f32_e32 v56, 0xbb800000, v114
	v_fmac_f32_e32 v100, 0xbb800000, v115
	s_waitcnt lgkmcnt(0)
	v_add_f32_e32 v117, v68, v104
	v_mov_b32_e32 v104, v65
	v_mov_b32_e32 v65, v70
	v_pk_mul_f32 v[68:69], v[104:105], v[104:105]
	v_pk_mul_f32 v[70:71], v[64:65], v[64:65]
	v_fmac_f32_e32 v101, 0xbb800000, v115
	v_pk_mov_b32 v[106:107], v[70:71], v[68:69] op_sel:[1,0]
	v_mov_b32_e32 v71, v69
	v_pk_add_f32 v[68:69], v[106:107], v[70:71]
	v_mov_b32_e32 v106, v63
	v_mov_b32_e32 v107, v73
	v_mov_b32_e32 v63, v72
	v_add_f32_e32 v118, v68, v69
	v_pk_mul_f32 v[68:69], v[106:107], v[106:107]
	v_pk_mul_f32 v[70:71], v[62:63], v[62:63]
	v_fmac_f32_e32 v55, 0xbb800000, v115
	v_pk_mov_b32 v[72:73], v[70:71], v[68:69] op_sel:[1,0]
	v_mov_b32_e32 v71, v69
	v_pk_add_f32 v[68:69], v[72:73], v[70:71]
	v_pk_mul_f32 v[70:71], v[60:61], v[60:61]
	v_add_f32_e32 v111, v68, v69
	v_pk_mul_f32 v[68:69], v[108:109], v[108:109]
	v_fmac_f32_e32 v54, 0xbb800000, v115
	v_pk_mov_b32 v[72:73], v[70:71], v[68:69] op_sel:[1,0]
	v_mov_b32_e32 v71, v69
	v_pk_add_f32 v[68:69], v[72:73], v[70:71]
	v_pk_mul_f32 v[70:71], v[58:59], v[58:59]
	v_add_f32_e32 v112, v68, v69
	v_pk_mul_f32 v[68:69], v[94:95], v[94:95]
	v_fmac_f32_e32 v66, 0xbb800000, v116
	v_pk_mov_b32 v[72:73], v[70:71], v[68:69] op_sel:[1,0]
	v_mov_b32_e32 v71, v69
	v_pk_add_f32 v[68:69], v[72:73], v[70:71]
	v_mov_b32_e32 v72, v57
	v_mov_b32_e32 v73, v99
	v_mov_b32_e32 v57, v98
	v_add_f32_e32 v113, v68, v69
	v_pk_mul_f32 v[68:69], v[72:73], v[72:73]
	v_pk_mul_f32 v[70:71], v[56:57], v[56:57]
	v_fmac_f32_e32 v67, 0xbb800000, v116
	v_pk_mov_b32 v[96:97], v[70:71], v[68:69] op_sel:[1,0]
	v_mov_b32_e32 v71, v69
	v_pk_add_f32 v[68:69], v[96:97], v[70:71]
	v_mov_b32_e32 v70, v55
	v_mov_b32_e32 v71, v101
	v_mov_b32_e32 v55, v100
	v_add_f32_e32 v114, v68, v69
	v_pk_mul_f32 v[68:69], v[70:71], v[70:71]
	v_pk_mul_f32 v[96:97], v[54:55], v[54:55]
	v_fmac_f32_e32 v53, 0xbb800000, v116
	v_pk_mov_b32 v[98:99], v[96:97], v[68:69] op_sel:[1,0]
	v_mov_b32_e32 v97, v69
	v_pk_add_f32 v[68:69], v[98:99], v[96:97]
	v_fmac_f32_e32 v52, 0xbb800000, v116
	v_add_f32_e32 v115, v68, v69
	v_mov_b32_e32 v68, v53
	v_mov_b32_e32 v69, v67
	v_mov_b32_e32 v53, v66
	v_pk_mul_f32 v[96:97], v[68:69], v[68:69]
	v_pk_mul_f32 v[66:67], v[52:53], v[52:53]
	v_fmac_f32_e32 v102, 0xbb800000, v117
	v_pk_mov_b32 v[98:99], v[66:67], v[96:97] op_sel:[1,0]
	v_mov_b32_e32 v67, v97
	v_pk_add_f32 v[66:67], v[98:99], v[66:67]
	v_fmac_f32_e32 v103, 0xbb800000, v117
	v_fmac_f32_e32 v51, 0xbb800000, v117
	v_add_f32_e32 v116, v66, v67
	v_fmac_f32_e32 v50, 0xbb800000, v117
	v_mov_b32_e32 v66, v51
	v_mov_b32_e32 v67, v103
	v_mov_b32_e32 v51, v102
	v_pk_mul_f32 v[96:97], v[66:67], v[66:67]
	v_pk_mul_f32 v[98:99], v[50:51], v[50:51]
	ds_bpermute_b32 v102, v213, v115
	v_pk_mov_b32 v[100:101], v[98:99], v[96:97] op_sel:[1,0]
	v_mov_b32_e32 v99, v97
	v_pk_add_f32 v[96:97], v[100:101], v[98:99]
	ds_bpermute_b32 v98, v213, v111
	v_add_f32_e32 v96, v96, v97
	ds_bpermute_b32 v97, v213, v118
	ds_bpermute_b32 v99, v213, v112
	ds_bpermute_b32 v100, v213, v113
	s_waitcnt lgkmcnt(3)
	v_add_f32_e32 v98, v111, v98
	ds_bpermute_b32 v111, v213, v96
	s_waitcnt lgkmcnt(3)
	v_add_f32_e32 v97, v118, v97
	s_waitcnt lgkmcnt(2)
	v_add_f32_e32 v99, v112, v99
	s_waitcnt lgkmcnt(1)
	v_add_f32_e32 v100, v113, v100
	ds_bpermute_b32 v101, v213, v114
	s_waitcnt lgkmcnt(1)
	v_add_f32_e32 v96, v96, v111
	ds_bpermute_b32 v111, v214, v97
	v_add_f32_e32 v102, v115, v102
	ds_bpermute_b32 v103, v213, v116
	s_waitcnt lgkmcnt(2)
	v_add_f32_e32 v101, v114, v101
	s_waitcnt lgkmcnt(1)
	v_add_f32_e32 v97, v97, v111
	ds_bpermute_b32 v111, v214, v98
	s_waitcnt lgkmcnt(1)
	v_add_f32_e32 v103, v116, v103
	s_waitcnt lgkmcnt(0)
	v_add_f32_e32 v98, v98, v111
	ds_bpermute_b32 v111, v214, v99
	s_waitcnt lgkmcnt(0)
	v_add_f32_e32 v99, v99, v111
	ds_bpermute_b32 v111, v214, v100
	s_waitcnt lgkmcnt(0)
	v_add_f32_e32 v100, v100, v111
	ds_bpermute_b32 v111, v214, v101
	s_waitcnt lgkmcnt(0)
	v_add_f32_e32 v101, v101, v111
	ds_bpermute_b32 v111, v214, v102
	s_waitcnt lgkmcnt(0)
	v_add_f32_e32 v102, v102, v111
	ds_bpermute_b32 v111, v214, v103
	s_waitcnt lgkmcnt(0)
	v_add_f32_e32 v103, v103, v111
	ds_bpermute_b32 v111, v214, v96
	s_waitcnt lgkmcnt(0)
	v_add_f32_e32 v96, v96, v111
	ds_bpermute_b32 v111, v91, v97
	s_waitcnt lgkmcnt(0)
	v_add_f32_e32 v97, v97, v111
	ds_bpermute_b32 v111, v91, v98
	s_waitcnt lgkmcnt(0)
	v_add_f32_e32 v98, v98, v111
	ds_bpermute_b32 v111, v91, v99
	s_waitcnt lgkmcnt(0)
	v_add_f32_e32 v99, v99, v111
	ds_bpermute_b32 v111, v91, v100
	s_waitcnt lgkmcnt(0)
	v_add_f32_e32 v100, v100, v111
	ds_bpermute_b32 v111, v91, v101
	s_waitcnt lgkmcnt(0)
	v_add_f32_e32 v101, v101, v111
	ds_bpermute_b32 v111, v91, v102
	s_waitcnt lgkmcnt(0)
	v_add_f32_e32 v102, v102, v111
	ds_bpermute_b32 v111, v91, v103
	s_waitcnt lgkmcnt(0)
	v_add_f32_e32 v103, v103, v111
	ds_bpermute_b32 v111, v91, v96
	s_waitcnt lgkmcnt(0)
	v_add_f32_e32 v96, v96, v111
	ds_bpermute_b32 v111, v92, v97
	s_waitcnt lgkmcnt(0)
	v_add_f32_e32 v97, v97, v111
	ds_bpermute_b32 v111, v92, v98
	s_waitcnt lgkmcnt(0)
	v_add_f32_e32 v98, v98, v111
	ds_bpermute_b32 v111, v92, v99
	s_waitcnt lgkmcnt(0)
	v_add_f32_e32 v99, v99, v111
	ds_bpermute_b32 v111, v92, v100
	s_waitcnt lgkmcnt(0)
	v_add_f32_e32 v100, v100, v111
	ds_bpermute_b32 v111, v92, v101
	s_waitcnt lgkmcnt(0)
	v_add_f32_e32 v101, v101, v111
	ds_bpermute_b32 v111, v92, v102
	s_waitcnt lgkmcnt(0)
	v_add_f32_e32 v102, v102, v111
	ds_bpermute_b32 v111, v92, v103
	s_waitcnt lgkmcnt(0)
; #define LAS __attribute__((address_space(3)))
; __device__ __forceinline__ unsigned pk2(float lo, float hi) { unsigned r; asm("v_cvt_pk_bf16_f32 %0, %1, %2" : "=v"(r) : "v"(lo), "v"(hi)); return r; }
; __device__ __forceinline__ float sigmoidf_(float x) { return fast_rcp(1.0f + fast_exp2(-1.4426950408889634f * x)); }
; __device__ __forceinline__ float rsq(float x) { return __builtin_amdgcn_rsqf(x); }
; __device__ __forceinline__ void mixer_chunk(KP p, LAS unsigned char* lds, int l, int chunk) {
;     ...
;             for (int i = 0; i < 8; ++i) { x[i] = x[i] - s[i] * (1.0f / 256.0f); s[i] = (x[i][0] * x[i][0] + x[i][1] * x[i][1]) + (x[i][2] * x[i][2] + x[i][3] * x[i][3]); }
; #pragma unroll
;             for (int o = 1; o < 64; o <<= 1)
; #pragma unroll
;                 for (int i = 0; i < 8; ++i) s[i] += __shfl_xor(s[i], o);
; #pragma unroll
;             for (int i = 0; i < 8; ++i) {
;                 const float rstd = rsq(s[i] * (1.0f / 256.0f) + EPS);
;                 f32x4 y = x[i] * rstd * lg + lb;
; #pragma unroll
;                 for (int j = 0; j < 4; ++j) y[j] = y[j] * sigmoidf_(y[j]);
;                 u32x2 o; o.x = pk2(y[0], y[1]); o.y = pk2(y[2], y[3]); *(LAS u32x2*)(CO + (16 * w + 8 * half + i) * YLD + 4 * lane) = o;
	v_add_f32_e32 v103, v103, v111
	ds_bpermute_b32 v111, v92, v96
	s_waitcnt lgkmcnt(0)
	v_add_f32_e32 v96, v96, v111
	ds_bpermute_b32 v111, v207, v97
	s_waitcnt lgkmcnt(0)
	v_add_f32_e32 v97, v97, v111
	ds_bpermute_b32 v111, v207, v98
	s_waitcnt lgkmcnt(0)
	v_add_f32_e32 v98, v98, v111
	ds_bpermute_b32 v111, v207, v99
	s_waitcnt lgkmcnt(0)
	v_add_f32_e32 v99, v99, v111
	ds_bpermute_b32 v111, v207, v100
	s_waitcnt lgkmcnt(0)
	v_add_f32_e32 v100, v100, v111
	ds_bpermute_b32 v111, v207, v101
	s_waitcnt lgkmcnt(0)
	v_add_f32_e32 v101, v101, v111
	ds_bpermute_b32 v111, v207, v102
	s_waitcnt lgkmcnt(0)
	v_add_f32_e32 v102, v102, v111
	ds_bpermute_b32 v111, v207, v103
	s_waitcnt lgkmcnt(0)
	v_add_f32_e32 v103, v103, v111
	ds_bpermute_b32 v111, v207, v96
	s_waitcnt lgkmcnt(0)
	v_add_f32_e32 v96, v96, v111
	ds_bpermute_b32 v111, v208, v97
	s_waitcnt lgkmcnt(0)
	v_add_f32_e32 v97, v97, v111
	ds_bpermute_b32 v111, v208, v98
	s_waitcnt lgkmcnt(0)
	v_add_f32_e32 v98, v98, v111
	ds_bpermute_b32 v111, v208, v99
	s_waitcnt lgkmcnt(0)
	v_add_f32_e32 v99, v99, v111
	ds_bpermute_b32 v111, v208, v100
	s_waitcnt lgkmcnt(0)
	v_add_f32_e32 v100, v100, v111
	ds_bpermute_b32 v111, v208, v101
	s_waitcnt lgkmcnt(0)
	v_add_f32_e32 v101, v101, v111
	ds_bpermute_b32 v111, v208, v102
	s_waitcnt lgkmcnt(0)
	v_add_f32_e32 v102, v102, v111
	ds_bpermute_b32 v111, v208, v103
	s_waitcnt lgkmcnt(0)
	v_add_f32_e32 v103, v103, v111
	ds_bpermute_b32 v111, v208, v96
	s_waitcnt lgkmcnt(0)
	v_add_f32_e32 v111, v96, v111
	v_fmamk_f32 v96, v97, 0x3b800000, v189
	v_rsq_f32_e32 v96, v96
	s_nop 0
	v_pk_mul_f32 v[64:65], v[64:65], v[96:97] op_sel_hi:[1,0]
	s_waitcnt vmcnt(16)
	v_pk_fma_f32 v[64:65], v[42:43], v[64:65], v[46:47]
	v_pk_mul_f32 v[96:97], v[104:105], v[96:97] op_sel_hi:[1,0]
	v_mul_f32_e32 v104, 0xbfb8aa3b, v64
	v_exp_f32_e32 v104, v104
	v_pk_fma_f32 v[96:97], v[44:45], v[96:97], v[48:49]
	v_add_f32_e32 v104, 1.0, v104
	v_rcp_f32_e32 v104, v104
	s_nop 0
	v_mul_f32_e32 v64, v64, v104
	v_mul_f32_e32 v104, 0xbfb8aa3b, v65
	v_exp_f32_e32 v104, v104
	s_nop 0
	v_add_f32_e32 v104, 1.0, v104
	v_rcp_f32_e32 v104, v104
	s_nop 0
	v_mul_f32_e32 v65, v65, v104
	v_mul_f32_e32 v104, 0xbfb8aa3b, v96
	v_exp_f32_e32 v104, v104
	v_cvt_pk_bf16_f32 v64, v64, v65
	s_nop 0
	v_add_f32_e32 v104, 1.0, v104
	v_rcp_f32_e32 v104, v104
	s_nop 0
	v_mul_f32_e32 v96, v96, v104
	v_mul_f32_e32 v104, 0xbfb8aa3b, v97
	v_exp_f32_e32 v104, v104
	s_nop 0
	v_add_f32_e32 v104, 1.0, v104
	v_rcp_f32_e32 v104, v104
	s_nop 0
	v_mul_f32_e32 v97, v97, v104
	v_cvt_pk_bf16_f32 v65, v96, v97
	v_fmamk_f32 v96, v98, 0x3b800000, v189
	v_rsq_f32_e32 v96, v96
	s_nop 0
	v_pk_mul_f32 v[62:63], v[62:63], v[96:97] op_sel_hi:[1,0]
	s_nop 0
	v_pk_fma_f32 v[62:63], v[42:43], v[62:63], v[46:47]
	v_pk_mul_f32 v[96:97], v[106:107], v[96:97] op_sel_hi:[1,0]
	v_mul_f32_e32 v98, 0xbfb8aa3b, v62
	v_exp_f32_e32 v98, v98
	v_pk_fma_f32 v[96:97], v[44:45], v[96:97], v[48:49]
	v_add_f32_e32 v98, 1.0, v98
	v_rcp_f32_e32 v98, v98
	s_nop 0
	v_mul_f32_e32 v62, v62, v98
	v_mul_f32_e32 v98, 0xbfb8aa3b, v63
	v_exp_f32_e32 v98, v98
	s_nop 0
	v_add_f32_e32 v98, 1.0, v98
	v_rcp_f32_e32 v98, v98
	s_nop 0
	v_mul_f32_e32 v63, v63, v98
	v_mul_f32_e32 v98, 0xbfb8aa3b, v96
	v_exp_f32_e32 v98, v98
	v_cvt_pk_bf16_f32 v62, v62, v63
	s_nop 0
	v_add_f32_e32 v98, 1.0, v98
	v_rcp_f32_e32 v98, v98
	s_nop 0
	v_mul_f32_e32 v96, v96, v98
	v_mul_f32_e32 v98, 0xbfb8aa3b, v97
	v_exp_f32_e32 v98, v98
	s_nop 0
	v_add_f32_e32 v98, 1.0, v98
	v_rcp_f32_e32 v98, v98
	s_nop 0
	v_mul_f32_e32 v97, v97, v98
	v_cvt_pk_bf16_f32 v63, v96, v97
	ds_write2_b64 v110, v[64:65], v[62:63] offset1:66
	v_fmamk_f32 v62, v99, 0x3b800000, v189
	v_rsq_f32_e32 v62, v62
	s_nop 0
	v_pk_mul_f32 v[60:61], v[60:61], v[62:63] op_sel_hi:[1,0]
	s_nop 0
	v_pk_fma_f32 v[60:61], v[42:43], v[60:61], v[46:47]
	v_pk_mul_f32 v[62:63], v[108:109], v[62:63] op_sel_hi:[1,0]
	v_mul_f32_e32 v64, 0xbfb8aa3b, v60
	v_exp_f32_e32 v64, v64
	v_pk_fma_f32 v[62:63], v[44:45], v[62:63], v[48:49]
	v_add_f32_e32 v64, 1.0, v64
	v_rcp_f32_e32 v64, v64
	s_nop 0
	v_mul_f32_e32 v60, v60, v64
	v_mul_f32_e32 v64, 0xbfb8aa3b, v61
	v_exp_f32_e32 v64, v64
	s_nop 0
	v_add_f32_e32 v64, 1.0, v64
	v_rcp_f32_e32 v64, v64
	s_nop 0
	v_mul_f32_e32 v61, v61, v64
	v_mul_f32_e32 v64, 0xbfb8aa3b, v62
	v_exp_f32_e32 v64, v64
	v_cvt_pk_bf16_f32 v60, v60, v61
	s_nop 0
	v_add_f32_e32 v64, 1.0, v64
	v_rcp_f32_e32 v64, v64
	s_nop 0
	v_mul_f32_e32 v62, v62, v64
	v_mul_f32_e32 v64, 0xbfb8aa3b, v63
	v_exp_f32_e32 v64, v64
	s_nop 0
	v_add_f32_e32 v64, 1.0, v64
	v_rcp_f32_e32 v64, v64
	s_nop 0
	v_mul_f32_e32 v63, v63, v64
	v_cvt_pk_bf16_f32 v61, v62, v63
	v_fmamk_f32 v62, v100, 0x3b800000, v189
	v_rsq_f32_e32 v62, v62
	s_nop 0
	v_pk_mul_f32 v[58:59], v[58:59], v[62:63] op_sel_hi:[1,0]
	s_nop 0
	v_pk_fma_f32 v[58:59], v[42:43], v[58:59], v[46:47]
	v_pk_mul_f32 v[62:63], v[94:95], v[62:63] op_sel_hi:[1,0]
	v_mul_f32_e32 v64, 0xbfb8aa3b, v58
	v_exp_f32_e32 v64, v64
	v_pk_fma_f32 v[62:63], v[44:45], v[62:63], v[48:49]
	v_add_f32_e32 v64, 1.0, v64
	v_rcp_f32_e32 v64, v64
	s_nop 0
	v_mul_f32_e32 v58, v58, v64
	v_mul_f32_e32 v64, 0xbfb8aa3b, v59
	v_exp_f32_e32 v64, v64
	s_nop 0
	v_add_f32_e32 v64, 1.0, v64
	v_rcp_f32_e32 v64, v64
	s_nop 0
	v_mul_f32_e32 v59, v59, v64
	v_mul_f32_e32 v64, 0xbfb8aa3b, v62
	v_exp_f32_e32 v64, v64
	v_cvt_pk_bf16_f32 v58, v58, v59
	s_nop 0
	v_add_f32_e32 v64, 1.0, v64
	v_rcp_f32_e32 v64, v64
	s_nop 0
	v_mul_f32_e32 v62, v62, v64
	v_mul_f32_e32 v64, 0xbfb8aa3b, v63
	v_exp_f32_e32 v64, v64
	s_nop 0
	v_add_f32_e32 v64, 1.0, v64
	v_rcp_f32_e32 v64, v64
	s_nop 0
	v_mul_f32_e32 v63, v63, v64
	v_cvt_pk_bf16_f32 v59, v62, v63
; #define LAS __attribute__((address_space(3)))
; __device__ __forceinline__ unsigned pk2(float lo, float hi) { unsigned r; asm("v_cvt_pk_bf16_f32 %0, %1, %2" : "=v"(r) : "v"(lo), "v"(hi)); return r; }
; __device__ __forceinline__ float sigmoidf_(float x) { return fast_rcp(1.0f + fast_exp2(-1.4426950408889634f * x)); }
; __device__ __forceinline__ float rsq(float x) { return __builtin_amdgcn_rsqf(x); }
; __device__ __forceinline__ void mixer_chunk(KP p, LAS unsigned char* lds, int l, int chunk) {
;     ...
;             for (int i = 0; i < 8; ++i) {
;                 const float rstd = rsq(s[i] * (1.0f / 256.0f) + EPS);
;                 f32x4 y = x[i] * rstd * lg + lb;
; #pragma unroll
;                 for (int j = 0; j < 4; ++j) y[j] = y[j] * sigmoidf_(y[j]);
;                 u32x2 o; o.x = pk2(y[0], y[1]); o.y = pk2(y[2], y[3]); *(LAS u32x2*)(CO + (16 * w + 8 * half + i) * YLD + 4 * lane) = o;
;             }
;         }
;     }
;     pin(sq); pin(sk);
; #pragma unroll
;     for (int i = 0; i < 6; ++i) { const int q = tid + 512 * i, r = q / 24, pc = q % 24; *(LAS u32x4*)(CQ + r * CQLD + 8 * pc) = sq[i]; }
; #pragma unroll
;     for (int i = 0; i < 4; ++i) { const int q = tid + 512 * i, r = q >> 4, pc = q & 15; *(LAS u32x4*)(CK + r * CKLD + 8 * pc) = sk[i]; }
	ds_write2_b64 v110, v[60:61], v[58:59] offset0:132 offset1:198
	v_fmamk_f32 v58, v101, 0x3b800000, v189
	v_rsq_f32_e32 v58, v58
	s_nop 0
	v_pk_mul_f32 v[56:57], v[56:57], v[58:59] op_sel_hi:[1,0]
	s_nop 0
	v_pk_fma_f32 v[56:57], v[42:43], v[56:57], v[46:47]
	v_pk_mul_f32 v[58:59], v[72:73], v[58:59] op_sel_hi:[1,0]
	v_mul_f32_e32 v60, 0xbfb8aa3b, v56
	v_exp_f32_e32 v60, v60
	v_pk_fma_f32 v[58:59], v[44:45], v[58:59], v[48:49]
	v_add_f32_e32 v60, 1.0, v60
	v_rcp_f32_e32 v60, v60
	s_nop 0
	v_mul_f32_e32 v56, v56, v60
	v_mul_f32_e32 v60, 0xbfb8aa3b, v57
	v_exp_f32_e32 v60, v60
	s_nop 0
	v_add_f32_e32 v60, 1.0, v60
	v_rcp_f32_e32 v60, v60
	s_nop 0
	v_mul_f32_e32 v57, v57, v60
	v_mul_f32_e32 v60, 0xbfb8aa3b, v58
	v_exp_f32_e32 v60, v60
	v_cvt_pk_bf16_f32 v56, v56, v57
	s_nop 0
	v_add_f32_e32 v60, 1.0, v60
	v_rcp_f32_e32 v60, v60
	s_nop 0
	v_mul_f32_e32 v58, v58, v60
	v_mul_f32_e32 v60, 0xbfb8aa3b, v59
	v_exp_f32_e32 v60, v60
	s_nop 0
	v_add_f32_e32 v60, 1.0, v60
	v_rcp_f32_e32 v60, v60
	s_nop 0
	v_mul_f32_e32 v59, v59, v60
	v_cvt_pk_bf16_f32 v57, v58, v59
	v_fmamk_f32 v58, v102, 0x3b800000, v189
	v_rsq_f32_e32 v58, v58
	s_nop 0
	v_pk_mul_f32 v[54:55], v[54:55], v[58:59] op_sel_hi:[1,0]
	s_nop 0
	v_pk_fma_f32 v[54:55], v[42:43], v[54:55], v[46:47]
	v_pk_mul_f32 v[58:59], v[70:71], v[58:59] op_sel_hi:[1,0]
	v_mul_f32_e32 v60, 0xbfb8aa3b, v54
	v_exp_f32_e32 v60, v60
	v_pk_fma_f32 v[58:59], v[44:45], v[58:59], v[48:49]
	v_add_f32_e32 v60, 1.0, v60
	v_rcp_f32_e32 v60, v60
	s_nop 0
	v_mul_f32_e32 v54, v54, v60
	v_mul_f32_e32 v60, 0xbfb8aa3b, v55
	v_exp_f32_e32 v60, v60
	s_nop 0
	v_add_f32_e32 v60, 1.0, v60
	v_rcp_f32_e32 v60, v60
	s_nop 0
	v_mul_f32_e32 v55, v55, v60
	v_mul_f32_e32 v60, 0xbfb8aa3b, v58
	v_exp_f32_e32 v60, v60
	v_cvt_pk_bf16_f32 v54, v54, v55
	s_nop 0
	v_add_f32_e32 v60, 1.0, v60
	v_rcp_f32_e32 v60, v60
	s_nop 0
	v_mul_f32_e32 v58, v58, v60
	v_mul_f32_e32 v60, 0xbfb8aa3b, v59
	v_exp_f32_e32 v60, v60
	s_nop 0
	v_add_f32_e32 v60, 1.0, v60
	v_rcp_f32_e32 v60, v60
	s_nop 0
	v_mul_f32_e32 v59, v59, v60
	v_cvt_pk_bf16_f32 v55, v58, v59
	ds_write2_b64 v93, v[56:57], v[54:55] offset0:8 offset1:74
	v_fmamk_f32 v54, v103, 0x3b800000, v189
	v_rsq_f32_e32 v54, v54
	s_nop 0
	v_pk_mul_f32 v[52:53], v[52:53], v[54:55] op_sel_hi:[1,0]
	s_nop 0
	v_pk_fma_f32 v[52:53], v[42:43], v[52:53], v[46:47]
	v_pk_mul_f32 v[54:55], v[68:69], v[54:55] op_sel_hi:[1,0]
	v_mul_f32_e32 v56, 0xbfb8aa3b, v52
	v_exp_f32_e32 v56, v56
	v_pk_fma_f32 v[54:55], v[44:45], v[54:55], v[48:49]
	v_add_f32_e32 v56, 1.0, v56
	v_rcp_f32_e32 v56, v56
	s_nop 0
	v_mul_f32_e32 v52, v52, v56
	v_mul_f32_e32 v56, 0xbfb8aa3b, v53
	v_exp_f32_e32 v56, v56
	s_nop 0
	v_add_f32_e32 v56, 1.0, v56
	v_rcp_f32_e32 v56, v56
	s_nop 0
	v_mul_f32_e32 v53, v53, v56
	v_mul_f32_e32 v56, 0xbfb8aa3b, v54
	v_exp_f32_e32 v56, v56
	v_cvt_pk_bf16_f32 v52, v52, v53
	s_nop 0
	v_add_f32_e32 v56, 1.0, v56
	v_rcp_f32_e32 v56, v56
	s_nop 0
	v_mul_f32_e32 v54, v54, v56
	v_mul_f32_e32 v56, 0xbfb8aa3b, v55
	v_exp_f32_e32 v56, v56
	s_nop 0
	v_add_f32_e32 v56, 1.0, v56
	v_rcp_f32_e32 v56, v56
	s_nop 0
	v_mul_f32_e32 v55, v55, v56
	v_cvt_pk_bf16_f32 v53, v54, v55
	v_fmamk_f32 v54, v111, 0x3b800000, v189
	v_rsq_f32_e32 v54, v54
	s_nop 0
	v_pk_mul_f32 v[50:51], v[50:51], v[54:55] op_sel_hi:[1,0]
	s_nop 0
	v_pk_fma_f32 v[50:51], v[42:43], v[50:51], v[46:47]
	v_pk_mul_f32 v[54:55], v[66:67], v[54:55] op_sel_hi:[1,0]
	v_mul_f32_e32 v56, 0xbfb8aa3b, v50
	v_exp_f32_e32 v56, v56
	v_pk_fma_f32 v[54:55], v[44:45], v[54:55], v[48:49]
	v_add_f32_e32 v56, 1.0, v56
	v_rcp_f32_e32 v56, v56
	s_nop 0
	v_mul_f32_e32 v50, v50, v56
	v_mul_f32_e32 v56, 0xbfb8aa3b, v51
	v_exp_f32_e32 v56, v56
	s_nop 0
	v_add_f32_e32 v56, 1.0, v56
	v_rcp_f32_e32 v56, v56
	s_nop 0
	v_mul_f32_e32 v51, v51, v56
	v_mul_f32_e32 v56, 0xbfb8aa3b, v54
	v_exp_f32_e32 v56, v56
	v_cvt_pk_bf16_f32 v50, v50, v51
	s_nop 0
	v_add_f32_e32 v56, 1.0, v56
	v_rcp_f32_e32 v56, v56
	s_nop 0
	v_mul_f32_e32 v54, v54, v56
	v_mul_f32_e32 v56, 0xbfb8aa3b, v55
	v_exp_f32_e32 v56, v56
	s_nop 0
	v_add_f32_e32 v56, 1.0, v56
	v_rcp_f32_e32 v56, v56
	s_nop 0
	v_mul_f32_e32 v55, v55, v56
	v_cvt_pk_bf16_f32 v51, v54, v55
	ds_write2_b64 v93, v[52:53], v[50:51] offset0:140 offset1:206
	s_cbranch_vccz .LBB0_297
	s_movk_i32 s6, 0x190
	v_mul_lo_u32 v0, v74, s6
	v_lshlrev_b32_e32 v42, 4, v75
	v_add3_u32 v0, 0, v0, v42
	ds_write_b128 v0, v[2:5]
	v_mul_lo_u32 v0, v76, s6
	v_lshlrev_b32_e32 v2, 4, v77
	v_add3_u32 v0, 0, v0, v2
	ds_write_b128 v0, v[6:9]
	v_mul_lo_u32 v0, v78, s6
	v_lshlrev_b32_e32 v2, 4, v79
	v_add3_u32 v0, 0, v0, v2
	ds_write_b128 v0, v[10:13]
	v_mul_lo_u32 v0, v80, s6
	v_lshlrev_b32_e32 v2, 4, v81
	v_add3_u32 v0, 0, v0, v2
	ds_write_b128 v0, v[14:17]
	v_mul_lo_u32 v0, v82, s6
	v_lshlrev_b32_e32 v2, 4, v83
	v_add3_u32 v0, 0, v0, v2
	ds_write_b128 v0, v[18:21]
	v_mul_lo_u32 v0, v84, s6
	v_lshlrev_b32_e32 v2, 4, v85
	v_add3_u32 v0, 0, v0, v2
	ds_write_b128 v0, v[22:25]
	v_lshl_add_u32 v0, v87, 1, 0
	v_mad_u64_u32 v[2:3], s[6:7], v86, s64, v[0:1]
	ds_write_b128 v2, v[26:29] offset:51200
	v_mad_u64_u32 v[2:3], s[6:7], v88, s64, v[0:1]
	ds_write_b128 v2, v[30:33] offset:51200
	v_mad_u64_u32 v[2:3], s[6:7], v89, s64, v[0:1]
	v_and_b32_e32 v217, 15, v204
	ds_write_b128 v2, v[34:37] offset:51200
	v_mad_u64_u32 v[2:3], s[6:7], v90, s64, v[0:1]
	s_lshl_b32 s42, s55, 5
	ds_write_b128 v2, v[38:41] offset:51200
	v_or_b32_e32 v2, s42, v217
	v_ashrrev_i32_e32 v3, 31, v2
	v_readlane_b32 s6, v252, 8
	v_lshlrev_b64 v[2:3], 9, v[2:3]
	v_readlane_b32 s7, v252, 9
	v_and_b32_e32 v0, 48, v205
	s_waitcnt lgkmcnt(0)
	v_lshl_add_u64 v[2:3], s[6:7], 0, v[2:3]
	v_lshl_add_u64 v[6:7], v[2:3], 0, v[0:1]
	s_barrier
; #define LAS __attribute__((address_space(3)))
; __device__ __forceinline__ f32x4 mfma16(bf16x8 a, bf16x8 b, f32x4 c) { return __builtin_amdgcn_mfma_f32_16x16x32_bf16(a, b, c, 0, 0, 0); }
; template <int NKS, int NNT>
; __device__ __forceinline__ void wgemm(f32x4 (&acc)[8][NNT], const LAS bf16_t* A, const int lda, const bf16_t* Bp, const int ldb) {
;     u32x4 bf[NNT][NKS];
; #pragma unroll
;     for (int nt = 0; nt < NNT; ++nt) ldfr(bf[nt], Bp + (size_t)(16 * nt) * ldb);
; #pragma unroll
;     for (int nt = 0; nt < NNT; ++nt) pin(bf[nt]);
; #pragma unroll
;     for (int mt = 0; mt < 8; ++mt) {
;         bf16x8 af[NKS];
; #pragma unroll
;         for (int ks = 0; ks < NKS; ++ks) af[ks] = *(const LAS bf16x8*)(A + (16 * mt) * lda + 32 * ks);
; #pragma unroll
;         for (int nt = 0; nt < NNT; ++nt) { f32x4 a = (f32x4){0.f, 0.f, 0.f, 0.f};
; #pragma unroll
;             for (int ks = 0; ks < NKS; ++ks) a = mfma16(as_bf16x8(bf[nt][ks]), af[ks], a);
;             acc[mt][nt] = a; }
;     }
; __device__ __forceinline__ void mixer_chunk(KP p, LAS unsigned char* lds, int l, int chunk) {
;     ...
;     wgemm<8, 2>(accc, CO + fr * YLD + 8 * fq, YLD, (const bf16_t*)(ws + OFF_PW + l * SZ_PW) + (size_t)(32 * w + fr) * 256 + 8 * fq, 256);
	s_waitcnt vmcnt(0)
	v_mov_b64_e32 v[118:119], v[120:121]
	v_mov_b64_e32 v[120:121], v[122:123]
	v_mov_b64_e32 v[114:115], v[124:125]
	v_mov_b64_e32 v[116:117], v[126:127]
	v_mov_b64_e32 v[110:111], v[128:129]
	v_mov_b64_e32 v[112:113], v[130:131]
	v_mov_b64_e32 v[106:107], v[132:133]
	v_mov_b64_e32 v[108:109], v[134:135]
	v_mov_b64_e32 v[102:103], v[136:137]
	v_mov_b64_e32 v[104:105], v[138:139]
	v_mov_b64_e32 v[90:91], v[140:141]
	v_mov_b64_e32 v[92:93], v[142:143]
	v_mov_b64_e32 v[86:87], v[144:145]
	v_mov_b64_e32 v[88:89], v[146:147]
	v_mov_b64_e32 v[2:3], v[148:149]
	v_mov_b64_e32 v[4:5], v[150:151]
	v_add_co_u32_e32 v6, vcc, s39, v6
	v_mov_b32_e32 v10, s69
	s_nop 0
	v_addc_co_u32_e32 v7, vcc, 0, v7, vcc
	v_mov_b64_e32 v[94:95], v[152:153]
	v_mov_b64_e32 v[96:97], v[154:155]
	v_mov_b64_e32 v[98:99], v[168:169]
	v_mov_b64_e32 v[100:101], v[170:171]
	v_mov_b64_e32 v[82:83], v[172:173]
	v_mov_b64_e32 v[84:85], v[174:175]
	v_mov_b64_e32 v[78:79], v[176:177]
	v_mov_b64_e32 v[80:81], v[178:179]
	v_mov_b64_e32 v[74:75], v[180:181]
	v_mov_b64_e32 v[76:77], v[182:183]
	v_mov_b64_e32 v[70:71], v[184:185]
	v_mov_b64_e32 v[72:73], v[186:187]
	v_mov_b64_e32 v[66:67], v[226:227]
	v_mov_b64_e32 v[68:69], v[228:229]
	s_nop 0
	v_mov_b64_e32 v[6:7], v[230:231]
	v_mov_b64_e32 v[8:9], v[232:233]
	v_mad_u32_u24 v219, v217, s67, v10
	v_add_u32_e32 v0, v219, v0
	v_lshlrev_b32_e32 v220, 5, v217
	v_readlane_b32 s6, v254, 20
	s_movk_i32 s18, 0x190
	v_cmp_gt_u32_e64 s[40:41], 16, v205
	v_add_u32_e32 v215, s6, v220
	v_lshl_add_u32 v216, s55, 2, v215
	s_waitcnt vmcnt(8)
	s_waitcnt vmcnt(0)
	ds_read_b128 v[10:13], v0
	ds_read_b128 v[14:17], v0 offset:64
	ds_read_b128 v[22:25], v0 offset:8448
	ds_read_b128 v[26:29], v0 offset:8512
	s_waitcnt lgkmcnt(3)
	v_mfma_f32_16x16x32_bf16 v[18:21], v[118:121], v[10:13], 0
	v_mfma_f32_16x16x32_bf16 v[10:13], v[94:97], v[10:13], 0
	s_waitcnt lgkmcnt(1)
	v_mfma_f32_16x16x32_bf16 v[30:33], v[118:121], v[22:25], 0
	v_mfma_f32_16x16x32_bf16 v[22:25], v[94:97], v[22:25], 0
	v_mfma_f32_16x16x32_bf16 v[18:21], v[114:117], v[14:17], v[18:21]
	v_mfma_f32_16x16x32_bf16 v[10:13], v[98:101], v[14:17], v[10:13]
	s_waitcnt lgkmcnt(0)
	v_mfma_f32_16x16x32_bf16 v[14:17], v[114:117], v[26:29], v[30:33]
	v_mfma_f32_16x16x32_bf16 v[22:25], v[98:101], v[26:29], v[22:25]
	ds_read_b128 v[26:29], v0 offset:128
	s_nop 0
	ds_read_b128 v[30:33], v0 offset:192
	s_waitcnt lgkmcnt(1)
	v_mfma_f32_16x16x32_bf16 v[18:21], v[110:113], v[26:29], v[18:21]
	v_mfma_f32_16x16x32_bf16 v[10:13], v[82:85], v[26:29], v[10:13]
	ds_read_b128 v[26:29], v0 offset:8576
	ds_read_b128 v[34:37], v0 offset:8640
	s_waitcnt lgkmcnt(1)
	v_mfma_f32_16x16x32_bf16 v[14:17], v[110:113], v[26:29], v[14:17]
	v_mfma_f32_16x16x32_bf16 v[22:25], v[82:85], v[26:29], v[22:25]
	v_mfma_f32_16x16x32_bf16 v[18:21], v[106:109], v[30:33], v[18:21]
	v_mfma_f32_16x16x32_bf16 v[10:13], v[78:81], v[30:33], v[10:13]
	ds_read_b128 v[26:29], v0 offset:256
	ds_read_b128 v[30:33], v0 offset:320
	s_waitcnt lgkmcnt(2)
	v_mfma_f32_16x16x32_bf16 v[14:17], v[106:109], v[34:37], v[14:17]
	v_mfma_f32_16x16x32_bf16 v[22:25], v[78:81], v[34:37], v[22:25]
	s_waitcnt lgkmcnt(1)
	v_mfma_f32_16x16x32_bf16 v[18:21], v[102:105], v[26:29], v[18:21]
	v_mfma_f32_16x16x32_bf16 v[10:13], v[74:77], v[26:29], v[10:13]
	ds_read_b128 v[26:29], v0 offset:8704
	ds_read_b128 v[34:37], v0 offset:8768
	s_waitcnt lgkmcnt(1)
	v_mfma_f32_16x16x32_bf16 v[14:17], v[102:105], v[26:29], v[14:17]
	v_mfma_f32_16x16x32_bf16 v[22:25], v[74:77], v[26:29], v[22:25]
	v_mfma_f32_16x16x32_bf16 v[18:21], v[90:93], v[30:33], v[18:21]
	v_mfma_f32_16x16x32_bf16 v[10:13], v[70:73], v[30:33], v[10:13]
	ds_read_b128 v[26:29], v0 offset:384
	ds_read_b128 v[30:33], v0 offset:448
	s_waitcnt lgkmcnt(2)
	v_mfma_f32_16x16x32_bf16 v[14:17], v[90:93], v[34:37], v[14:17]
	s_waitcnt lgkmcnt(1)
	v_mfma_f32_16x16x32_bf16 v[18:21], v[86:89], v[26:29], v[18:21]
	v_mfma_f32_16x16x32_bf16 v[10:13], v[66:69], v[26:29], v[10:13]
	ds_read_b128 v[26:29], v0 offset:8832
	ds_read_b128 v[38:41], v0 offset:8896
	v_mfma_f32_16x16x32_bf16 v[22:25], v[70:73], v[34:37], v[22:25]
	s_waitcnt lgkmcnt(1)
	v_mfma_f32_16x16x32_bf16 v[14:17], v[86:89], v[26:29], v[14:17]
	v_mfma_f32_16x16x32_bf16 v[58:61], v[6:9], v[30:33], v[10:13]
	v_mfma_f32_16x16x32_bf16 v[10:13], v[66:69], v[26:29], v[22:25]
	s_waitcnt lgkmcnt(0)
	v_mfma_f32_16x16x32_bf16 v[54:57], v[2:5], v[38:41], v[14:17]
	v_mfma_f32_16x16x32_bf16 v[50:53], v[6:9], v[38:41], v[10:13]
	s_nop 4
	ds_read_b128 v[10:13], v0 offset:16896
	ds_read_b128 v[14:17], v0 offset:16960
	ds_read_b128 v[22:25], v0 offset:17024
	ds_read_b128 v[26:29], v0 offset:17088
	v_mfma_f32_16x16x32_bf16 v[62:65], v[2:5], v[30:33], v[18:21]
	ds_read_b128 v[30:33], v0 offset:17152
	ds_read_b128 v[34:37], v0 offset:17216
	ds_read_b128 v[38:41], v0 offset:17280
	ds_read_b128 v[42:45], v0 offset:17344
	s_waitcnt lgkmcnt(7)
	v_mfma_f32_16x16x32_bf16 v[18:21], v[118:121], v[10:13], 0
	v_mfma_f32_16x16x32_bf16 v[10:13], v[94:97], v[10:13], 0
	s_waitcnt lgkmcnt(6)
	v_mfma_f32_16x16x32_bf16 v[18:21], v[114:117], v[14:17], v[18:21]
	v_mfma_f32_16x16x32_bf16 v[10:13], v[98:101], v[14:17], v[10:13]
	s_waitcnt lgkmcnt(5)
	v_mfma_f32_16x16x32_bf16 v[18:21], v[110:113], v[22:25], v[18:21]
	v_mfma_f32_16x16x32_bf16 v[10:13], v[82:85], v[22:25], v[10:13]
	s_waitcnt lgkmcnt(4)
	v_mfma_f32_16x16x32_bf16 v[18:21], v[106:109], v[26:29], v[18:21]
	v_mfma_f32_16x16x32_bf16 v[10:13], v[78:81], v[26:29], v[10:13]
	s_waitcnt lgkmcnt(3)
	v_mfma_f32_16x16x32_bf16 v[18:21], v[102:105], v[30:33], v[18:21]
	v_mfma_f32_16x16x32_bf16 v[10:13], v[74:77], v[30:33], v[10:13]
	s_waitcnt lgkmcnt(2)
; #define LAS __attribute__((address_space(3)))
; __device__ __forceinline__ f32x4 mfma16(bf16x8 a, bf16x8 b, f32x4 c) { return __builtin_amdgcn_mfma_f32_16x16x32_bf16(a, b, c, 0, 0, 0); }
; template <int NKS, int NNT>
; __device__ __forceinline__ void wgemm(f32x4 (&acc)[8][NNT], const LAS bf16_t* A, const int lda, const bf16_t* Bp, const int ldb) {
;     ...
;     for (int mt = 0; mt < 8; ++mt) {
;         bf16x8 af[NKS];
; #pragma unroll
;         for (int ks = 0; ks < NKS; ++ks) af[ks] = *(const LAS bf16x8*)(A + (16 * mt) * lda + 32 * ks);
; #pragma unroll
;         for (int nt = 0; nt < NNT; ++nt) { f32x4 a = (f32x4){0.f, 0.f, 0.f, 0.f};
; #pragma unroll
;             for (int ks = 0; ks < NKS; ++ks) a = mfma16(as_bf16x8(bf[nt][ks]), af[ks], a);
;             acc[mt][nt] = a; }
;     }
	v_mfma_f32_16x16x32_bf16 v[18:21], v[90:93], v[34:37], v[18:21]
	v_mfma_f32_16x16x32_bf16 v[10:13], v[70:73], v[34:37], v[10:13]
	s_waitcnt lgkmcnt(1)
	v_mfma_f32_16x16x32_bf16 v[18:21], v[86:89], v[38:41], v[18:21]
	v_mfma_f32_16x16x32_bf16 v[10:13], v[66:69], v[38:41], v[10:13]
	s_waitcnt lgkmcnt(0)
	v_mfma_f32_16x16x32_bf16 v[46:49], v[2:5], v[42:45], v[18:21]
	v_mfma_f32_16x16x32_bf16 v[42:45], v[6:9], v[42:45], v[10:13]
	s_nop 4
	ds_read_b128 v[10:13], v0 offset:25344
	ds_read_b128 v[14:17], v0 offset:25408
	ds_read_b128 v[22:25], v0 offset:25472
	ds_read_b128 v[26:29], v0 offset:25536
	ds_read_b128 v[30:33], v0 offset:25600
	ds_read_b128 v[34:37], v0 offset:25664
	s_waitcnt lgkmcnt(5)
	v_mfma_f32_16x16x32_bf16 v[18:21], v[118:121], v[10:13], 0
	ds_read_b128 v[122:125], v0 offset:25728
	ds_read_b128 v[126:129], v0 offset:25792
	v_mfma_f32_16x16x32_bf16 v[10:13], v[94:97], v[10:13], 0
	s_waitcnt lgkmcnt(6)
	v_mfma_f32_16x16x32_bf16 v[10:13], v[98:101], v[14:17], v[10:13]
	v_mfma_f32_16x16x32_bf16 v[18:21], v[114:117], v[14:17], v[18:21]
	s_waitcnt lgkmcnt(5)
	v_mfma_f32_16x16x32_bf16 v[10:13], v[82:85], v[22:25], v[10:13]
	v_mfma_f32_16x16x32_bf16 v[18:21], v[110:113], v[22:25], v[18:21]
	s_waitcnt lgkmcnt(4)
	v_mfma_f32_16x16x32_bf16 v[10:13], v[78:81], v[26:29], v[10:13]
	v_mfma_f32_16x16x32_bf16 v[18:21], v[106:109], v[26:29], v[18:21]
	s_waitcnt lgkmcnt(3)
	v_mfma_f32_16x16x32_bf16 v[10:13], v[74:77], v[30:33], v[10:13]
	v_mfma_f32_16x16x32_bf16 v[18:21], v[102:105], v[30:33], v[18:21]
	s_waitcnt lgkmcnt(2)
	v_mfma_f32_16x16x32_bf16 v[10:13], v[70:73], v[34:37], v[10:13]
	v_mfma_f32_16x16x32_bf16 v[18:21], v[90:93], v[34:37], v[18:21]
	s_waitcnt lgkmcnt(1)
	v_mfma_f32_16x16x32_bf16 v[10:13], v[66:69], v[122:125], v[10:13]
	v_mfma_f32_16x16x32_bf16 v[18:21], v[86:89], v[122:125], v[18:21]
	s_waitcnt lgkmcnt(0)
	v_mfma_f32_16x16x32_bf16 v[34:37], v[6:9], v[126:129], v[10:13]
	s_nop 4
	ds_read_b128 v[10:13], v0 offset:33792
	ds_read_b128 v[14:17], v0 offset:33856
	ds_read_b128 v[22:25], v0 offset:33920
	ds_read_b128 v[26:29], v0 offset:33984
	v_mfma_f32_16x16x32_bf16 v[38:41], v[2:5], v[126:129], v[18:21]
	ds_read_b128 v[122:125], v0 offset:34048
	ds_read_b128 v[126:129], v0 offset:34112
	ds_read_b128 v[130:133], v0 offset:34176
	ds_read_b128 v[134:137], v0 offset:34240
	s_waitcnt lgkmcnt(7)
	v_mfma_f32_16x16x32_bf16 v[18:21], v[118:121], v[10:13], 0
	v_mfma_f32_16x16x32_bf16 v[10:13], v[94:97], v[10:13], 0
	s_waitcnt lgkmcnt(6)
	v_mfma_f32_16x16x32_bf16 v[10:13], v[98:101], v[14:17], v[10:13]
	v_mfma_f32_16x16x32_bf16 v[18:21], v[114:117], v[14:17], v[18:21]
	s_waitcnt lgkmcnt(5)
	v_mfma_f32_16x16x32_bf16 v[10:13], v[82:85], v[22:25], v[10:13]
	v_mfma_f32_16x16x32_bf16 v[18:21], v[110:113], v[22:25], v[18:21]
	s_waitcnt lgkmcnt(4)
	v_mfma_f32_16x16x32_bf16 v[10:13], v[78:81], v[26:29], v[10:13]
	v_mfma_f32_16x16x32_bf16 v[18:21], v[106:109], v[26:29], v[18:21]
	s_waitcnt lgkmcnt(3)
	v_mfma_f32_16x16x32_bf16 v[10:13], v[74:77], v[122:125], v[10:13]
	v_mfma_f32_16x16x32_bf16 v[18:21], v[102:105], v[122:125], v[18:21]
	s_waitcnt lgkmcnt(2)
	v_mfma_f32_16x16x32_bf16 v[10:13], v[70:73], v[126:129], v[10:13]
	v_mfma_f32_16x16x32_bf16 v[18:21], v[90:93], v[126:129], v[18:21]
	s_waitcnt lgkmcnt(1)
	v_mfma_f32_16x16x32_bf16 v[10:13], v[66:69], v[130:133], v[10:13]
	v_mfma_f32_16x16x32_bf16 v[18:21], v[86:89], v[130:133], v[18:21]
	s_waitcnt lgkmcnt(0)
	v_mfma_f32_16x16x32_bf16 v[26:29], v[6:9], v[134:137], v[10:13]
	s_nop 4
	ds_read_b128 v[10:13], v0 offset:42240
	ds_read_b128 v[14:17], v0 offset:42304
	ds_read_b128 v[122:125], v0 offset:42368
	ds_read_b128 v[126:129], v0 offset:42432
	v_mfma_f32_16x16x32_bf16 v[30:33], v[2:5], v[134:137], v[18:21]
	ds_read_b128 v[130:133], v0 offset:42496
	ds_read_b128 v[134:137], v0 offset:42560
	ds_read_b128 v[138:141], v0 offset:42624
	ds_read_b128 v[142:145], v0 offset:42688
	s_waitcnt lgkmcnt(7)
	v_mfma_f32_16x16x32_bf16 v[18:21], v[118:121], v[10:13], 0
	v_mfma_f32_16x16x32_bf16 v[10:13], v[94:97], v[10:13], 0
	s_waitcnt lgkmcnt(6)
	v_mfma_f32_16x16x32_bf16 v[18:21], v[114:117], v[14:17], v[18:21]
	v_mfma_f32_16x16x32_bf16 v[10:13], v[98:101], v[14:17], v[10:13]
	s_waitcnt lgkmcnt(5)
	v_mfma_f32_16x16x32_bf16 v[18:21], v[110:113], v[122:125], v[18:21]
	v_mfma_f32_16x16x32_bf16 v[10:13], v[82:85], v[122:125], v[10:13]
	s_waitcnt lgkmcnt(4)
; #define LAS __attribute__((address_space(3)))
; __device__ __forceinline__ f32x4 mfma16(bf16x8 a, bf16x8 b, f32x4 c) { return __builtin_amdgcn_mfma_f32_16x16x32_bf16(a, b, c, 0, 0, 0); }
; template <int NKS, int NNT>
; __device__ __forceinline__ void wgemm(f32x4 (&acc)[8][NNT], const LAS bf16_t* A, const int lda, const bf16_t* Bp, const int ldb) {
;     ...
;     for (int mt = 0; mt < 8; ++mt) {
;         bf16x8 af[NKS];
; #pragma unroll
;         for (int ks = 0; ks < NKS; ++ks) af[ks] = *(const LAS bf16x8*)(A + (16 * mt) * lda + 32 * ks);
; #pragma unroll
;         for (int nt = 0; nt < NNT; ++nt) { f32x4 a = (f32x4){0.f, 0.f, 0.f, 0.f};
; #pragma unroll
;             for (int ks = 0; ks < NKS; ++ks) a = mfma16(as_bf16x8(bf[nt][ks]), af[ks], a);
;             acc[mt][nt] = a; }
;     }
; template <int NNT>
; __device__ __forceinline__ void part_sumsq(const f32x4 (&acc)[8][NNT], LAS float* part, int w, int fr, int fq) {
; #pragma unroll
;     for (int mt = 0; mt < 8; ++mt) { float s = 0.f;
; #pragma unroll
;         for (int nt = 0; nt < NNT; ++nt) s += (acc[mt][nt][0] * acc[mt][nt][0] + acc[mt][nt][1] * acc[mt][nt][1]) + (acc[mt][nt][2] * acc[mt][nt][2] + acc[mt][nt][3] * acc[mt][nt][3]);
;         s += __shfl_xor(s, 16); s += __shfl_xor(s, 32);
;         if (fq == 0) part[(16 * mt + fr) * 8 + w] = s; }
	v_mfma_f32_16x16x32_bf16 v[18:21], v[106:109], v[126:129], v[18:21]
	v_mfma_f32_16x16x32_bf16 v[10:13], v[78:81], v[126:129], v[10:13]
	s_waitcnt lgkmcnt(3)
	v_mfma_f32_16x16x32_bf16 v[18:21], v[102:105], v[130:133], v[18:21]
	v_mfma_f32_16x16x32_bf16 v[10:13], v[74:77], v[130:133], v[10:13]
	s_waitcnt lgkmcnt(2)
	v_mfma_f32_16x16x32_bf16 v[18:21], v[90:93], v[134:137], v[18:21]
	v_mfma_f32_16x16x32_bf16 v[10:13], v[70:73], v[134:137], v[10:13]
	s_waitcnt lgkmcnt(1)
	v_mfma_f32_16x16x32_bf16 v[18:21], v[86:89], v[138:141], v[18:21]
	v_mfma_f32_16x16x32_bf16 v[10:13], v[66:69], v[138:141], v[10:13]
	s_waitcnt lgkmcnt(0)
	v_mfma_f32_16x16x32_bf16 v[22:25], v[2:5], v[142:145], v[18:21]
	v_mfma_f32_16x16x32_bf16 v[18:21], v[6:9], v[142:145], v[10:13]
	s_nop 4
	ds_read_b128 v[10:13], v0 offset:50688
	ds_read_b128 v[122:125], v0 offset:50752
	ds_read_b128 v[126:129], v0 offset:50816
	ds_read_b128 v[130:133], v0 offset:50880
	ds_read_b128 v[134:137], v0 offset:50944
	ds_read_b128 v[138:141], v0 offset:51008
	s_waitcnt lgkmcnt(5)
	v_mfma_f32_16x16x32_bf16 v[14:17], v[118:121], v[10:13], 0
	ds_read_b128 v[142:145], v0 offset:51072
	ds_read_b128 v[146:149], v0 offset:51136
	v_mfma_f32_16x16x32_bf16 v[10:13], v[94:97], v[10:13], 0
	s_waitcnt lgkmcnt(6)
	v_mfma_f32_16x16x32_bf16 v[14:17], v[114:117], v[122:125], v[14:17]
	v_mfma_f32_16x16x32_bf16 v[10:13], v[98:101], v[122:125], v[10:13]
	s_waitcnt lgkmcnt(5)
	v_mfma_f32_16x16x32_bf16 v[14:17], v[110:113], v[126:129], v[14:17]
	v_mfma_f32_16x16x32_bf16 v[10:13], v[82:85], v[126:129], v[10:13]
	ds_read_b128 v[122:125], v0 offset:59136
	ds_read_b128 v[126:129], v0 offset:59200
	s_waitcnt lgkmcnt(1)
	v_mfma_f32_16x16x32_bf16 v[118:121], v[118:121], v[122:125], 0
	v_mfma_f32_16x16x32_bf16 v[14:17], v[106:109], v[130:133], v[14:17]
	v_mfma_f32_16x16x32_bf16 v[10:13], v[78:81], v[130:133], v[10:13]
	s_waitcnt lgkmcnt(0)
	v_mfma_f32_16x16x32_bf16 v[114:117], v[114:117], v[126:129], v[118:121]
	s_nop 3
	ds_read_b128 v[118:121], v0 offset:59264
	ds_read_b128 v[130:133], v0 offset:59328
	s_waitcnt lgkmcnt(1)
	v_mfma_f32_16x16x32_bf16 v[110:113], v[110:113], v[118:121], v[114:117]
	s_waitcnt lgkmcnt(0)
	v_mfma_f32_16x16x32_bf16 v[106:109], v[106:109], v[130:133], v[110:113]
	s_nop 5
	ds_read_b128 v[110:113], v0 offset:59392
	ds_read_b128 v[114:117], v0 offset:59456
	v_mfma_f32_16x16x32_bf16 v[14:17], v[102:105], v[134:137], v[14:17]
	s_waitcnt lgkmcnt(1)
	v_mfma_f32_16x16x32_bf16 v[102:105], v[102:105], v[110:113], v[106:109]
	v_mfma_f32_16x16x32_bf16 v[14:17], v[90:93], v[138:141], v[14:17]
	s_waitcnt lgkmcnt(0)
	v_mfma_f32_16x16x32_bf16 v[90:93], v[90:93], v[114:117], v[102:105]
	s_nop 4
	ds_read_b128 v[102:105], v0 offset:59520
	ds_read_b128 v[106:109], v0 offset:59584
	v_mul_f32_e32 v0, v63, v63
	v_fmac_f32_e32 v0, v62, v62
	v_mfma_f32_16x16x32_bf16 v[14:17], v[86:89], v[142:145], v[14:17]
	s_waitcnt lgkmcnt(1)
	v_mfma_f32_16x16x32_bf16 v[86:89], v[86:89], v[102:105], v[90:93]
	v_mfma_f32_16x16x32_bf16 v[14:17], v[2:5], v[146:149], v[14:17]
	s_waitcnt lgkmcnt(0)
	v_mfma_f32_16x16x32_bf16 v[2:5], v[2:5], v[106:109], v[86:89]
	v_mfma_f32_16x16x32_bf16 v[86:89], v[94:97], v[122:125], 0
	v_mfma_f32_16x16x32_bf16 v[86:89], v[98:101], v[126:129], v[86:89]
	v_mfma_f32_16x16x32_bf16 v[82:85], v[82:85], v[118:121], v[86:89]
	v_mfma_f32_16x16x32_bf16 v[78:81], v[78:81], v[130:133], v[82:85]
	s_nop 5
	v_mul_f32_e32 v86, v65, v65
	v_fmac_f32_e32 v86, v64, v64
	v_add_f32_e32 v0, v0, v86
	v_mfma_f32_16x16x32_bf16 v[10:13], v[74:77], v[134:137], v[10:13]
	v_mul_f32_e32 v82, v59, v59
	v_fmac_f32_e32 v82, v58, v58
	v_mfma_f32_16x16x32_bf16 v[74:77], v[74:77], v[110:113], v[78:81]
	s_nop 2
	v_mul_f32_e32 v78, v61, v61
	v_fmac_f32_e32 v78, v60, v60
	v_add_f32_e32 v78, v82, v78
	v_mfma_f32_16x16x32_bf16 v[10:13], v[70:73], v[138:141], v[10:13]
	v_add_f32_e32 v0, v0, v78
	v_mfma_f32_16x16x32_bf16 v[70:73], v[70:73], v[114:117], v[74:77]
	s_nop 2
	ds_bpermute_b32 v74, v207, v0
	v_mfma_f32_16x16x32_bf16 v[10:13], v[66:69], v[142:145], v[10:13]
	s_waitcnt lgkmcnt(0)
	v_add_f32_e32 v0, v0, v74
	v_mfma_f32_16x16x32_bf16 v[68:71], v[66:69], v[102:105], v[70:73]
	ds_bpermute_b32 v66, v208, v0
	v_mfma_f32_16x16x32_bf16 v[10:13], v[6:9], v[146:149], v[10:13]
	v_mfma_f32_16x16x32_bf16 v[6:9], v[6:9], v[106:109], v[68:71]
	s_and_saveexec_b64 s[6:7], s[40:41]
	s_cbranch_execz .LBB0_300
	s_waitcnt lgkmcnt(0)
	v_add_f32_e32 v0, v0, v66
	ds_write_b32 v216, v0
